# mixb scores: the 80 exec-masked validity/bias blocks rewritten branch-free (two unsigned range compares, fmac, mul, v_cndmask per element; bias reads use one base register with immediate offsets)
# speedup vs baseline: 1.0336x; 1.0025x over previous
; DI f32x16 mfma(bf16x8 a, bf16x8 b, f32x16 c) { return __builtin_amdgcn_mfma_f32_32x32x16_bf16(a, b, c, 0, 0, 0); }
; DI f32x16 zero16() { f32x16 z; for (int i = 0; i < 16; ++i) z[i] = 0.f; return z; }
; DI void phase_mixb(const Prm& p, unsigned char* smem_raw, int S, int lgS, int& base) {
;     ...
;     const int wt = t * 8 + wave;
;     const int hg = wt & 1, g = (wt >> 1) % 3, blk = wt / 6;
;     const int seq = blk >> (lgS - 5), b_in = blk & ((S >> 5) - 1);
;     const int lgd = 2 * g, L = S >> lgd;
;     const int lgbpr = lgS - lgd - 5;
;     const int res = b_in >> lgbpr, i0 = (b_in & ((1 << lgbpr) - 1)) << 5;
;     const int tokbase = seq * S + res;
;     const int hd = g * 2 + hg, hc = hd * 64;
;     const int qi = i0 + lr;
;     const int qtok = tokbase + (qi << lgd);
;     bf16x8 qf[4];
; #pragma unroll
;     for (int ks = 0; ks < 4; ++ks) qf[ks] = *(const bf16x8*)(p.bqkv + (size_t)qtok * 1152 + hc + ks * 16 + lh * 8);
;     f32x16 sc[5];
; #pragma unroll
;     for (int tt = 0; tt < 5; ++tt) {
;       int ik = i0 - 64 + 32 * tt + lr;
;       ik = min(max(ik, 0), L - 1);
;       const u16* kp = p.bqkv + (size_t)(tokbase + (ik << lgd)) * 1152 + 384 + hc + lh * 8;
;       sc[tt] = zero16();
; #pragma unroll
;       for (int ks = 0; ks < 4; ++ks) sc[tt] = mfma(*(const bf16x8*)(kp + ks * 16), qf[ks], sc[tt]);
;     }
.LBB0_1837:
	v_ashrrev_i32_e32 v2, 1, v128
	s_mov_b32 s2, 0x55555556
	v_mul_hi_i32 v3, v2, s2
	v_lshrrev_b32_e32 v4, 31, v3
	v_add_u32_e32 v3, v3, v4
	v_lshl_add_u32 v3, v3, 1, v3
	v_sub_u32_e32 v2, v2, v3
	v_mul_hi_i32 v3, v128, s82
	v_lshrrev_b32_e32 v4, 31, v3
	v_add_u32_e32 v3, v3, v4
	v_readlane_b32 s2, v254, 48
	v_lshlrev_b32_e32 v99, 1, v2
	v_or_b32_e32 v98, v99, v104
	v_ashrrev_i32_e32 v4, s2, v3
	v_readlane_b32 s2, v254, 50
	v_readlane_b32 s36, v253, 24
	v_lshlrev_b32_e32 v100, 6, v98
	v_and_b32_e32 v3, s2, v3
	v_readlane_b32 s2, v254, 51
	v_readlane_b32 s38, v253, 26
	v_readlane_b32 s39, v253, 27
	v_sub_u32_e32 v2, s2, v99
	v_add_u32_e32 v2, -5, v2
	s_waitcnt vmcnt(9)
	v_bfe_u32 v135, v3, 0, v2
	v_lshrrev_b32_e32 v5, v2, v3
	v_lshlrev_b32_e32 v133, 5, v135
	v_lshl_add_u32 v131, v4, s2, v5
	v_or_b32_e32 v97, v133, v95
	v_lshl_add_u32 v130, v97, v99, v131
	v_mov_b64_e32 v[6:7], s[38:39]
	s_movk_i32 s4, 0x900
	v_ashrrev_i32_e32 v101, 31, v100
	v_mad_i64_i32 v[2:3], s[2:3], v130, s4, v[6:7]
	v_lshlrev_b64 v[102:103], 1, v[100:101]
	v_lshl_add_u64 v[2:3], v[2:3], 0, v[102:103]
	v_readlane_b32 s2, v254, 49
	v_lshl_add_u64 v[8:9], v[2:3], 0, v[0:1]
	v_add_u32_e32 v14, v133, v105
	v_lshrrev_b32_e64 v134, v99, s2
	global_load_dwordx4 v[2:5], v[8:9], off
	global_load_dwordx4 v[90:93], v[8:9], off offset:32
	global_load_dwordx4 v[86:89], v[8:9], off offset:64
	global_load_dwordx4 v[82:85], v[8:9], off offset:96
	v_add_u32_e32 v132, -1, v134
	v_max_i32_e32 v8, 0, v14
	v_min_i32_e32 v8, v8, v132
	v_lshl_add_u32 v8, v8, v99, v131
	v_mad_i64_i32 v[8:9], s[2:3], v8, s4, v[6:7]
	v_lshl_add_u64 v[8:9], v[8:9], 0, v[102:103]
	v_lshl_add_u64 v[12:13], v[8:9], 0, v[0:1]
	global_load_dwordx4 v[144:147], v[12:13], off offset:768
	global_load_dwordx4 v[148:151], v[12:13], off offset:800
	global_load_dwordx4 v[152:155], v[12:13], off offset:832
	global_load_dwordx4 v[156:159], v[12:13], off offset:864
	v_max_i32_e32 v8, 0xffffffe0, v14
	v_add_u32_e32 v8, 32, v8
	v_min_i32_e32 v8, v8, v132
	v_lshl_add_u32 v8, v8, v99, v131
	v_mad_i64_i32 v[8:9], s[2:3], v8, s4, v[6:7]
	v_lshl_add_u64 v[8:9], v[8:9], 0, v[102:103]
	v_lshl_add_u64 v[136:137], v[8:9], 0, v[0:1]
	global_load_dwordx4 v[160:163], v[136:137], off offset:768
	global_load_dwordx4 v[164:167], v[136:137], off offset:800
	global_load_dwordx4 v[168:171], v[136:137], off offset:832
	global_load_dwordx4 v[172:175], v[136:137], off offset:864
	v_max_i32_e32 v8, 0xffffffc0, v14
	v_add_u32_e32 v8, 64, v8
	v_min_i32_e32 v8, v8, v132
	v_lshl_add_u32 v8, v8, v99, v131
	v_mad_i64_i32 v[8:9], s[2:3], v8, s4, v[6:7]
	v_lshl_add_u64 v[8:9], v[8:9], 0, v[102:103]
	v_lshl_add_u64 v[138:139], v[8:9], 0, v[0:1]
	global_load_dwordx4 v[176:179], v[138:139], off offset:768
	global_load_dwordx4 v[180:183], v[138:139], off offset:800
	global_load_dwordx4 v[184:187], v[138:139], off offset:832
	global_load_dwordx4 v[188:191], v[138:139], off offset:864
	v_max_i32_e32 v8, 0xffffffa0, v14
	v_add_u32_e32 v8, 0x60, v8
	v_min_i32_e32 v8, v8, v132
	v_lshl_add_u32 v8, v8, v99, v131
	v_mad_i64_i32 v[8:9], s[2:3], v8, s4, v[6:7]
	v_lshl_add_u64 v[8:9], v[8:9], 0, v[102:103]
	v_lshl_add_u64 v[140:141], v[8:9], 0, v[0:1]
	global_load_dwordx4 v[192:195], v[140:141], off offset:768
	global_load_dwordx4 v[196:199], v[140:141], off offset:800
	global_load_dwordx4 v[200:203], v[140:141], off offset:832
	global_load_dwordx4 v[204:207], v[140:141], off offset:864
	v_max_i32_e32 v8, 0xffffff80, v14
	v_add_u32_e32 v8, 0x80, v8
	v_min_i32_e32 v8, v8, v132
	v_lshl_add_u32 v8, v8, v99, v131
	v_mad_i64_i32 v[8:9], s[2:3], v8, s4, v[6:7]
	v_lshl_add_u64 v[8:9], v[8:9], 0, v[102:103]
	v_lshl_add_u64 v[142:143], v[8:9], 0, v[0:1]
	global_load_dwordx4 v[208:211], v[142:143], off offset:768
	global_load_dwordx4 v[212:215], v[142:143], off offset:800
	global_load_dwordx4 v[216:219], v[142:143], off offset:832
	global_load_dwordx4 v[220:223], v[142:143], off offset:864
	v_cmp_lt_u32_e32 vcc, 1, v135
	v_readlane_b32 s37, v253, 25
	v_readlane_b32 s40, v253, 28
	v_readlane_b32 s41, v253, 29
	v_readlane_b32 s42, v253, 30
	v_readlane_b32 s43, v253, 31
	v_readlane_b32 s44, v253, 32
	v_readlane_b32 s45, v253, 33
	v_readlane_b32 s46, v253, 34
	v_readlane_b32 s47, v253, 35
	v_readlane_b32 s48, v253, 36
	v_readlane_b32 s49, v253, 37
	v_readlane_b32 s50, v253, 38
	v_readlane_b32 s51, v253, 39
	s_waitcnt vmcnt(16)
	v_mfma_f32_32x32x16_bf16 v[66:81], v[144:147], v[2:5], 0
	v_mfma_f32_32x32x16_bf16 v[66:81], v[148:151], v[90:93], v[66:81]
	v_mfma_f32_32x32x16_bf16 v[66:81], v[152:155], v[86:89], v[66:81]
	v_mfma_f32_32x32x16_bf16 v[66:81], v[156:159], v[82:85], v[66:81]
	s_waitcnt vmcnt(12)
	v_mfma_f32_32x32x16_bf16 v[50:65], v[160:163], v[2:5], 0
	v_mfma_f32_32x32x16_bf16 v[50:65], v[164:167], v[90:93], v[50:65]
	v_mfma_f32_32x32x16_bf16 v[50:65], v[168:171], v[86:89], v[50:65]
	v_mfma_f32_32x32x16_bf16 v[50:65], v[172:175], v[82:85], v[50:65]
	s_waitcnt vmcnt(8)
	v_mfma_f32_32x32x16_bf16 v[34:49], v[176:179], v[2:5], 0
	v_mfma_f32_32x32x16_bf16 v[34:49], v[180:183], v[90:93], v[34:49]
	v_mfma_f32_32x32x16_bf16 v[34:49], v[184:187], v[86:89], v[34:49]
	v_mfma_f32_32x32x16_bf16 v[34:49], v[188:191], v[82:85], v[34:49]
	s_waitcnt vmcnt(4)
	v_mfma_f32_32x32x16_bf16 v[18:33], v[192:195], v[2:5], 0
	v_mfma_f32_32x32x16_bf16 v[18:33], v[196:199], v[90:93], v[18:33]
	v_mfma_f32_32x32x16_bf16 v[18:33], v[200:203], v[86:89], v[18:33]
	v_mfma_f32_32x32x16_bf16 v[18:33], v[204:207], v[82:85], v[18:33]
	s_waitcnt vmcnt(0)
; DI int rowmap(int r, int lh) { return (r & 3) + 8 * (r >> 2) + 4 * lh; }
; DI void phase_mixb(const Prm& p, unsigned char* smem_raw, int S, int lgS, int& base) {
;     ...
;     float mx = -1e30f;
; #pragma unroll
;     for (int tt = 0; tt < 5; ++tt)
; #pragma unroll
;       for (int r = 0; r < 16; ++r) {
;         const int ik = i0 - 64 + 32 * tt + rowmap(r, lh);
;         const int rel = ik - qi;
;         const bool valid = (rel >= -64) && (rel <= 64) && (ik >= 0) && (ik < L);
;         const int bi = min(max(rel + 64, 0), 128);
;         const float s = valid ? (sc[tt][r] * 0.125f + bt[hd * 129 + bi]) * LOG2E : -1e30f;
;         sc[tt][r] = s;
;         mx = fmaxf(mx, s);
;       }
	v_mfma_f32_32x32x16_bf16 v[2:17], v[208:211], v[2:5], 0
	v_mfma_f32_32x32x16_bf16 v[2:17], v[212:215], v[90:93], v[2:17]
	v_mfma_f32_32x32x16_bf16 v[2:17], v[216:219], v[86:89], v[2:17]
	v_mfma_f32_32x32x16_bf16 v[2:17], v[220:223], v[82:85], v[2:17]
	v_sub_u32_e32 v83, v94, v95
	v_mul_i32_i24_e32 v82, 0x204, v98
	v_lshl_add_u32 v82, v83, 2, v82
	ds_read_b32 v148, v82
	ds_read_b32 v149, v82 offset:4
	ds_read_b32 v150, v82 offset:8
	ds_read_b32 v151, v82 offset:12
	ds_read_b32 v152, v82 offset:32
	ds_read_b32 v153, v82 offset:36
	ds_read_b32 v154, v82 offset:40
	ds_read_b32 v155, v82 offset:44
	s_waitcnt lgkmcnt(7)
	ds_read_b32 v163, v82 offset:64
	ds_read_b32 v164, v82 offset:68
	ds_read_b32 v165, v82 offset:72
	ds_read_b32 v166, v82 offset:76
	ds_read_b32 v167, v82 offset:96
	ds_read_b32 v168, v82 offset:100
	ds_read_b32 v169, v82 offset:104
	ds_read_b32 v170, v82 offset:108
	s_waitcnt lgkmcnt(7)
	ds_read_b32 v171, v82 offset:128
	ds_read_b32 v172, v82 offset:132
	ds_read_b32 v173, v82 offset:136
	ds_read_b32 v174, v82 offset:140
	ds_read_b32 v175, v82 offset:160
	ds_read_b32 v176, v82 offset:164
	ds_read_b32 v177, v82 offset:168
	ds_read_b32 v178, v82 offset:172
	s_waitcnt lgkmcnt(7)
	ds_read_b32 v179, v82 offset:192
	ds_read_b32 v180, v82 offset:196
	ds_read_b32 v181, v82 offset:200
	ds_read_b32 v182, v82 offset:204
	ds_read_b32 v183, v82 offset:224
	ds_read_b32 v184, v82 offset:228
	ds_read_b32 v185, v82 offset:232
	ds_read_b32 v186, v82 offset:236
	s_waitcnt lgkmcnt(7)
	ds_read_b32 v187, v82 offset:256
	ds_read_b32 v188, v82 offset:260
	ds_read_b32 v189, v82 offset:264
	ds_read_b32 v190, v82 offset:268
	ds_read_b32 v191, v82 offset:288
	ds_read_b32 v192, v82 offset:292
	ds_read_b32 v193, v82 offset:296
	ds_read_b32 v194, v82 offset:300
	s_waitcnt lgkmcnt(7)
	ds_read_b32 v195, v82 offset:320
	ds_read_b32 v196, v82 offset:324
	ds_read_b32 v197, v82 offset:328
	ds_read_b32 v198, v82 offset:332
	ds_read_b32 v199, v82 offset:352
	ds_read_b32 v200, v82 offset:356
	ds_read_b32 v201, v82 offset:360
	ds_read_b32 v202, v82 offset:364
	s_waitcnt lgkmcnt(7)
	ds_read_b32 v203, v82 offset:384
	ds_read_b32 v204, v82 offset:388
	ds_read_b32 v205, v82 offset:392
	ds_read_b32 v206, v82 offset:396
	ds_read_b32 v207, v82 offset:416
	ds_read_b32 v208, v82 offset:420
	ds_read_b32 v209, v82 offset:424
	ds_read_b32 v210, v82 offset:428
	s_waitcnt lgkmcnt(7)
	ds_read_b32 v211, v82 offset:448
	ds_read_b32 v212, v82 offset:452
	ds_read_b32 v213, v82 offset:456
	ds_read_b32 v214, v82 offset:460
	ds_read_b32 v215, v82 offset:480
	ds_read_b32 v216, v82 offset:484
	ds_read_b32 v217, v82 offset:488
	ds_read_b32 v218, v82 offset:492
	s_waitcnt lgkmcnt(7)
	ds_read_b32 v219, v82 offset:512
	ds_read_b32 v220, v82 offset:516
	ds_read_b32 v221, v82 offset:520
	ds_read_b32 v222, v82 offset:524
	ds_read_b32 v223, v82 offset:544
	ds_read_b32 v226, v82 offset:548
	ds_read_b32 v227, v82 offset:552
	ds_read_b32 v228, v82 offset:556
	s_waitcnt lgkmcnt(7)
	ds_read_b32 v229, v82 offset:576
	ds_read_b32 v234, v82 offset:580
	ds_read_b32 v235, v82 offset:584
	ds_read_b32 v236, v82 offset:588
	ds_read_b32 v237, v82 offset:608
	ds_read_b32 v244, v82 offset:612
	ds_read_b32 v245, v82 offset:616
	ds_read_b32 v246, v82 offset:620
	s_waitcnt lgkmcnt(0)
	v_subrev_u32_e32 v85, 64, v133
	v_add_u32_e32 v85, v85, v94
	v_mov_b32_e32 v93, 0xf149f2ca
	v_add_u32_e32 v90, 0, v85
	v_cmp_gt_u32_e64 s[2:3], v134, v90
	v_add_u32_e32 v92, 0, v107
	v_cmp_gt_u32_e32 vcc, 0x81, v92
	v_fmac_f32_e32 v148, 0x3e000000, v66
	s_and_b64 vcc, vcc, s[2:3]
	v_mul_f32_e32 v148, 0x3fb8aa3b, v148
	v_cndmask_b32_e32 v84, v93, v148, vcc
	v_add_u32_e32 v90, 1, v85
	v_cmp_gt_u32_e64 s[2:3], v134, v90
	v_add_u32_e32 v92, 1, v107
	v_cmp_gt_u32_e32 vcc, 0x81, v92
	v_fmac_f32_e32 v149, 0x3e000000, v67
	s_and_b64 vcc, vcc, s[2:3]
	v_mul_f32_e32 v149, 0x3fb8aa3b, v149
	v_cndmask_b32_e32 v83, v93, v149, vcc
	v_add_u32_e32 v90, 2, v85
	v_cmp_gt_u32_e64 s[2:3], v134, v90
	v_add_u32_e32 v92, 2, v107
	v_cmp_gt_u32_e32 vcc, 0x81, v92
	v_fmac_f32_e32 v150, 0x3e000000, v68
	s_and_b64 vcc, vcc, s[2:3]
	v_mul_f32_e32 v150, 0x3fb8aa3b, v150
	v_cndmask_b32_e32 v86, v93, v150, vcc
	v_add_u32_e32 v90, 3, v85
	v_cmp_gt_u32_e64 s[2:3], v134, v90
	v_add_u32_e32 v92, 3, v107
	v_cmp_gt_u32_e32 vcc, 0x81, v92
	v_fmac_f32_e32 v151, 0x3e000000, v69
	s_and_b64 vcc, vcc, s[2:3]
	v_mul_f32_e32 v151, 0x3fb8aa3b, v151
	v_cndmask_b32_e32 v67, v93, v151, vcc
	v_add_u32_e32 v90, 8, v85
	v_cmp_gt_u32_e64 s[2:3], v134, v90
	v_add_u32_e32 v92, 8, v107
	v_cmp_gt_u32_e32 vcc, 0x81, v92
	v_fmac_f32_e32 v152, 0x3e000000, v70
	s_and_b64 vcc, vcc, s[2:3]
	v_mul_f32_e32 v152, 0x3fb8aa3b, v152
	v_cndmask_b32_e32 v69, v93, v152, vcc
	v_add_u32_e32 v90, 9, v85
	v_cmp_gt_u32_e64 s[2:3], v134, v90
	v_add_u32_e32 v92, 9, v107
	v_cmp_gt_u32_e32 vcc, 0x81, v92
	v_fmac_f32_e32 v153, 0x3e000000, v71
	s_and_b64 vcc, vcc, s[2:3]
	v_mul_f32_e32 v153, 0x3fb8aa3b, v153
	v_cndmask_b32_e32 v68, v93, v153, vcc
	v_add_u32_e32 v90, 10, v85
	v_cmp_gt_u32_e64 s[2:3], v134, v90
	v_add_u32_e32 v92, 10, v107
	v_cmp_gt_u32_e32 vcc, 0x81, v92
	v_fmac_f32_e32 v154, 0x3e000000, v72
	s_and_b64 vcc, vcc, s[2:3]
	v_mul_f32_e32 v154, 0x3fb8aa3b, v154
	v_cndmask_b32_e32 v71, v93, v154, vcc
	v_add_u32_e32 v90, 11, v85
	v_cmp_gt_u32_e64 s[2:3], v134, v90
	v_add_u32_e32 v92, 11, v107
	v_cmp_gt_u32_e32 vcc, 0x81, v92
	v_fmac_f32_e32 v155, 0x3e000000, v73
	s_and_b64 vcc, vcc, s[2:3]
	v_mul_f32_e32 v155, 0x3fb8aa3b, v155
	v_cndmask_b32_e32 v70, v93, v155, vcc
	v_add_u32_e32 v90, 16, v85
	v_cmp_gt_u32_e64 s[2:3], v134, v90
	v_add_u32_e32 v92, 16, v107
	v_cmp_gt_u32_e32 vcc, 0x81, v92
; DI int rowmap(int r, int lh) { return (r & 3) + 8 * (r >> 2) + 4 * lh; }
; DI void phase_mixb(const Prm& p, unsigned char* smem_raw, int S, int lgS, int& base) {
;     ...
;     float mx = -1e30f;
; #pragma unroll
;     for (int tt = 0; tt < 5; ++tt)
; #pragma unroll
;       for (int r = 0; r < 16; ++r) {
;         const int ik = i0 - 64 + 32 * tt + rowmap(r, lh);
;         const int rel = ik - qi;
;         const bool valid = (rel >= -64) && (rel <= 64) && (ik >= 0) && (ik < L);
;         const int bi = min(max(rel + 64, 0), 128);
;         const float s = valid ? (sc[tt][r] * 0.125f + bt[hd * 129 + bi]) * LOG2E : -1e30f;
;         sc[tt][r] = s;
;         mx = fmaxf(mx, s);
;       }
	v_fmac_f32_e32 v163, 0x3e000000, v74
	s_and_b64 vcc, vcc, s[2:3]
	v_mul_f32_e32 v163, 0x3fb8aa3b, v163
	v_cndmask_b32_e32 v73, v93, v163, vcc
	v_add_u32_e32 v90, 17, v85
	v_cmp_gt_u32_e64 s[2:3], v134, v90
	v_add_u32_e32 v92, 17, v107
	v_cmp_gt_u32_e32 vcc, 0x81, v92
	v_fmac_f32_e32 v164, 0x3e000000, v75
	s_and_b64 vcc, vcc, s[2:3]
	v_mul_f32_e32 v164, 0x3fb8aa3b, v164
	v_cndmask_b32_e32 v72, v93, v164, vcc
	v_add_u32_e32 v90, 18, v85
	v_cmp_gt_u32_e64 s[2:3], v134, v90
	v_add_u32_e32 v92, 18, v107
	v_cmp_gt_u32_e32 vcc, 0x81, v92
	v_fmac_f32_e32 v165, 0x3e000000, v76
	s_and_b64 vcc, vcc, s[2:3]
	v_mul_f32_e32 v165, 0x3fb8aa3b, v165
	v_cndmask_b32_e32 v75, v93, v165, vcc
	v_add_u32_e32 v90, 19, v85
	v_cmp_gt_u32_e64 s[2:3], v134, v90
	v_add_u32_e32 v92, 19, v107
	v_cmp_gt_u32_e32 vcc, 0x81, v92
	v_fmac_f32_e32 v166, 0x3e000000, v77
	s_and_b64 vcc, vcc, s[2:3]
	v_mul_f32_e32 v166, 0x3fb8aa3b, v166
	v_cndmask_b32_e32 v74, v93, v166, vcc
	v_add_u32_e32 v90, 24, v85
	v_cmp_gt_u32_e64 s[2:3], v134, v90
	v_add_u32_e32 v92, 24, v107
	v_cmp_gt_u32_e32 vcc, 0x81, v92
	v_fmac_f32_e32 v167, 0x3e000000, v78
	s_and_b64 vcc, vcc, s[2:3]
	v_mul_f32_e32 v167, 0x3fb8aa3b, v167
	v_cndmask_b32_e32 v77, v93, v167, vcc
	v_add_u32_e32 v90, 25, v85
	v_cmp_gt_u32_e64 s[2:3], v134, v90
	v_add_u32_e32 v92, 25, v107
	v_cmp_gt_u32_e32 vcc, 0x81, v92
	v_fmac_f32_e32 v168, 0x3e000000, v79
	s_and_b64 vcc, vcc, s[2:3]
	v_mul_f32_e32 v168, 0x3fb8aa3b, v168
	v_cndmask_b32_e32 v76, v93, v168, vcc
	v_add_u32_e32 v90, 26, v85
	v_cmp_gt_u32_e64 s[2:3], v134, v90
	v_add_u32_e32 v92, 26, v107
	v_cmp_gt_u32_e32 vcc, 0x81, v92
	v_fmac_f32_e32 v169, 0x3e000000, v80
	s_and_b64 vcc, vcc, s[2:3]
	v_mul_f32_e32 v169, 0x3fb8aa3b, v169
	v_cndmask_b32_e32 v79, v93, v169, vcc
	v_add_u32_e32 v90, 27, v85
	v_cmp_gt_u32_e64 s[2:3], v134, v90
	v_add_u32_e32 v92, 27, v107
	v_cmp_gt_u32_e32 vcc, 0x81, v92
	v_fmac_f32_e32 v170, 0x3e000000, v81
	s_and_b64 vcc, vcc, s[2:3]
	v_mul_f32_e32 v170, 0x3fb8aa3b, v170
	v_cndmask_b32_e32 v78, v93, v170, vcc
	v_add_u32_e32 v90, 32, v85
	v_cmp_gt_u32_e64 s[2:3], v134, v90
	v_add_u32_e32 v92, 32, v107
	v_cmp_gt_u32_e32 vcc, 0x81, v92
	v_fmac_f32_e32 v171, 0x3e000000, v50
	s_and_b64 vcc, vcc, s[2:3]
	v_mul_f32_e32 v171, 0x3fb8aa3b, v171
	v_cndmask_b32_e32 v81, v93, v171, vcc
	v_add_u32_e32 v90, 33, v85
	v_cmp_gt_u32_e64 s[2:3], v134, v90
	v_add_u32_e32 v92, 33, v107
	v_cmp_gt_u32_e32 vcc, 0x81, v92
	v_fmac_f32_e32 v172, 0x3e000000, v51
	s_and_b64 vcc, vcc, s[2:3]
	v_mul_f32_e32 v172, 0x3fb8aa3b, v172
	v_cndmask_b32_e32 v80, v93, v172, vcc
	v_add_u32_e32 v90, 34, v85
	v_cmp_gt_u32_e64 s[2:3], v134, v90
	v_add_u32_e32 v92, 34, v107
	v_cmp_gt_u32_e32 vcc, 0x81, v92
	v_fmac_f32_e32 v173, 0x3e000000, v52
	s_and_b64 vcc, vcc, s[2:3]
	v_mul_f32_e32 v173, 0x3fb8aa3b, v173
	v_cndmask_b32_e32 v51, v93, v173, vcc
	v_add_u32_e32 v90, 35, v85
	v_cmp_gt_u32_e64 s[2:3], v134, v90
	v_add_u32_e32 v92, 35, v107
	v_cmp_gt_u32_e32 vcc, 0x81, v92
	v_fmac_f32_e32 v174, 0x3e000000, v53
	s_and_b64 vcc, vcc, s[2:3]
	v_mul_f32_e32 v174, 0x3fb8aa3b, v174
	v_cndmask_b32_e32 v50, v93, v174, vcc
	v_add_u32_e32 v90, 40, v85
	v_cmp_gt_u32_e64 s[2:3], v134, v90
	v_add_u32_e32 v92, 40, v107
	v_cmp_gt_u32_e32 vcc, 0x81, v92
	v_fmac_f32_e32 v175, 0x3e000000, v54
	s_and_b64 vcc, vcc, s[2:3]
	v_mul_f32_e32 v175, 0x3fb8aa3b, v175
	v_cndmask_b32_e32 v53, v93, v175, vcc
	v_add_u32_e32 v90, 41, v85
	v_cmp_gt_u32_e64 s[2:3], v134, v90
	v_add_u32_e32 v92, 41, v107
	v_cmp_gt_u32_e32 vcc, 0x81, v92
	v_fmac_f32_e32 v176, 0x3e000000, v55
	s_and_b64 vcc, vcc, s[2:3]
	v_mul_f32_e32 v176, 0x3fb8aa3b, v176
	v_cndmask_b32_e32 v52, v93, v176, vcc
	v_add_u32_e32 v90, 42, v85
	v_cmp_gt_u32_e64 s[2:3], v134, v90
	v_add_u32_e32 v92, 42, v107
	v_cmp_gt_u32_e32 vcc, 0x81, v92
	v_fmac_f32_e32 v177, 0x3e000000, v56
	s_and_b64 vcc, vcc, s[2:3]
	v_mul_f32_e32 v177, 0x3fb8aa3b, v177
	v_cndmask_b32_e32 v55, v93, v177, vcc
	v_add_u32_e32 v90, 43, v85
	v_cmp_gt_u32_e64 s[2:3], v134, v90
	v_add_u32_e32 v92, 43, v107
	v_cmp_gt_u32_e32 vcc, 0x81, v92
	v_fmac_f32_e32 v178, 0x3e000000, v57
	s_and_b64 vcc, vcc, s[2:3]
	v_mul_f32_e32 v178, 0x3fb8aa3b, v178
	v_cndmask_b32_e32 v54, v93, v178, vcc
	v_add_u32_e32 v90, 48, v85
	v_cmp_gt_u32_e64 s[2:3], v134, v90
	v_add_u32_e32 v92, 48, v107
	v_cmp_gt_u32_e32 vcc, 0x81, v92
	v_fmac_f32_e32 v179, 0x3e000000, v58
	s_and_b64 vcc, vcc, s[2:3]
	v_mul_f32_e32 v179, 0x3fb8aa3b, v179
	v_cndmask_b32_e32 v57, v93, v179, vcc
	v_add_u32_e32 v90, 49, v85
	v_cmp_gt_u32_e64 s[2:3], v134, v90
	v_add_u32_e32 v92, 49, v107
	v_cmp_gt_u32_e32 vcc, 0x81, v92
	v_fmac_f32_e32 v180, 0x3e000000, v59
	s_and_b64 vcc, vcc, s[2:3]
	v_mul_f32_e32 v180, 0x3fb8aa3b, v180
	v_cndmask_b32_e32 v56, v93, v180, vcc
	v_add_u32_e32 v90, 50, v85
	v_cmp_gt_u32_e64 s[2:3], v134, v90
	v_add_u32_e32 v92, 50, v107
	v_cmp_gt_u32_e32 vcc, 0x81, v92
	v_fmac_f32_e32 v181, 0x3e000000, v60
	s_and_b64 vcc, vcc, s[2:3]
	v_mul_f32_e32 v181, 0x3fb8aa3b, v181
	v_cndmask_b32_e32 v59, v93, v181, vcc
	v_add_u32_e32 v90, 51, v85
	v_cmp_gt_u32_e64 s[2:3], v134, v90
	v_add_u32_e32 v92, 51, v107
	v_cmp_gt_u32_e32 vcc, 0x81, v92
	v_fmac_f32_e32 v182, 0x3e000000, v61
	s_and_b64 vcc, vcc, s[2:3]
	v_mul_f32_e32 v182, 0x3fb8aa3b, v182
	v_cndmask_b32_e32 v58, v93, v182, vcc
	v_add_u32_e32 v90, 56, v85
	v_cmp_gt_u32_e64 s[2:3], v134, v90
	v_add_u32_e32 v92, 56, v107
	v_cmp_gt_u32_e32 vcc, 0x81, v92
	v_fmac_f32_e32 v183, 0x3e000000, v62
	s_and_b64 vcc, vcc, s[2:3]
	v_mul_f32_e32 v183, 0x3fb8aa3b, v183
	v_cndmask_b32_e32 v61, v93, v183, vcc
	v_add_u32_e32 v90, 57, v85
	v_cmp_gt_u32_e64 s[2:3], v134, v90
	v_add_u32_e32 v92, 57, v107
	v_cmp_gt_u32_e32 vcc, 0x81, v92
; DI int rowmap(int r, int lh) { return (r & 3) + 8 * (r >> 2) + 4 * lh; }
; DI void phase_mixb(const Prm& p, unsigned char* smem_raw, int S, int lgS, int& base) {
;     ...
;     float mx = -1e30f;
; #pragma unroll
;     for (int tt = 0; tt < 5; ++tt)
; #pragma unroll
;       for (int r = 0; r < 16; ++r) {
;         const int ik = i0 - 64 + 32 * tt + rowmap(r, lh);
;         const int rel = ik - qi;
;         const bool valid = (rel >= -64) && (rel <= 64) && (ik >= 0) && (ik < L);
;         const int bi = min(max(rel + 64, 0), 128);
;         const float s = valid ? (sc[tt][r] * 0.125f + bt[hd * 129 + bi]) * LOG2E : -1e30f;
;         sc[tt][r] = s;
;         mx = fmaxf(mx, s);
;       }
	v_fmac_f32_e32 v184, 0x3e000000, v63
	s_and_b64 vcc, vcc, s[2:3]
	v_mul_f32_e32 v184, 0x3fb8aa3b, v184
	v_cndmask_b32_e32 v60, v93, v184, vcc
	v_add_u32_e32 v90, 58, v85
	v_cmp_gt_u32_e64 s[2:3], v134, v90
	v_add_u32_e32 v92, 58, v107
	v_cmp_gt_u32_e32 vcc, 0x81, v92
	v_fmac_f32_e32 v185, 0x3e000000, v64
	s_and_b64 vcc, vcc, s[2:3]
	v_mul_f32_e32 v185, 0x3fb8aa3b, v185
	v_cndmask_b32_e32 v63, v93, v185, vcc
	v_add_u32_e32 v90, 59, v85
	v_cmp_gt_u32_e64 s[2:3], v134, v90
	v_add_u32_e32 v92, 59, v107
	v_cmp_gt_u32_e32 vcc, 0x81, v92
	v_fmac_f32_e32 v186, 0x3e000000, v65
	s_and_b64 vcc, vcc, s[2:3]
	v_mul_f32_e32 v186, 0x3fb8aa3b, v186
	v_cndmask_b32_e32 v62, v93, v186, vcc
	v_add_u32_e32 v90, 64, v85
	v_cmp_gt_u32_e64 s[2:3], v134, v90
	v_add_u32_e32 v92, 64, v107
	v_cmp_gt_u32_e32 vcc, 0x81, v92
	v_fmac_f32_e32 v187, 0x3e000000, v34
	s_and_b64 vcc, vcc, s[2:3]
	v_mul_f32_e32 v187, 0x3fb8aa3b, v187
	v_cndmask_b32_e32 v65, v93, v187, vcc
	v_add_u32_e32 v90, 0x41, v85
	v_cmp_gt_u32_e64 s[2:3], v134, v90
	v_add_u32_e32 v92, 0x41, v107
	v_cmp_gt_u32_e32 vcc, 0x81, v92
	v_fmac_f32_e32 v188, 0x3e000000, v35
	s_and_b64 vcc, vcc, s[2:3]
	v_mul_f32_e32 v188, 0x3fb8aa3b, v188
	v_cndmask_b32_e32 v64, v93, v188, vcc
	v_add_u32_e32 v90, 0x42, v85
	v_cmp_gt_u32_e64 s[2:3], v134, v90
	v_add_u32_e32 v92, 0x42, v107
	v_cmp_gt_u32_e32 vcc, 0x81, v92
	v_fmac_f32_e32 v189, 0x3e000000, v36
	s_and_b64 vcc, vcc, s[2:3]
	v_mul_f32_e32 v189, 0x3fb8aa3b, v189
	v_cndmask_b32_e32 v35, v93, v189, vcc
	v_add_u32_e32 v90, 0x43, v85
	v_cmp_gt_u32_e64 s[2:3], v134, v90
	v_add_u32_e32 v92, 0x43, v107
	v_cmp_gt_u32_e32 vcc, 0x81, v92
	v_fmac_f32_e32 v190, 0x3e000000, v37
	s_and_b64 vcc, vcc, s[2:3]
	v_mul_f32_e32 v190, 0x3fb8aa3b, v190
	v_cndmask_b32_e32 v34, v93, v190, vcc
	v_add_u32_e32 v90, 0x48, v85
	v_cmp_gt_u32_e64 s[2:3], v134, v90
	v_add_u32_e32 v92, 0x48, v107
	v_cmp_gt_u32_e32 vcc, 0x81, v92
	v_fmac_f32_e32 v191, 0x3e000000, v38
	s_and_b64 vcc, vcc, s[2:3]
	v_mul_f32_e32 v191, 0x3fb8aa3b, v191
	v_cndmask_b32_e32 v87, v93, v191, vcc
	v_add_u32_e32 v90, 0x49, v85
	v_cmp_gt_u32_e64 s[2:3], v134, v90
	v_add_u32_e32 v92, 0x49, v107
	v_cmp_gt_u32_e32 vcc, 0x81, v92
	v_fmac_f32_e32 v192, 0x3e000000, v39
	s_and_b64 vcc, vcc, s[2:3]
	v_mul_f32_e32 v192, 0x3fb8aa3b, v192
	v_cndmask_b32_e32 v88, v93, v192, vcc
	v_add_u32_e32 v90, 0x4a, v85
	v_cmp_gt_u32_e64 s[2:3], v134, v90
	v_add_u32_e32 v92, 0x4a, v107
	v_cmp_gt_u32_e32 vcc, 0x81, v92
	v_fmac_f32_e32 v193, 0x3e000000, v40
	s_and_b64 vcc, vcc, s[2:3]
	v_mul_f32_e32 v193, 0x3fb8aa3b, v193
	v_cndmask_b32_e32 v89, v93, v193, vcc
	v_add_u32_e32 v90, 0x4b, v85
	v_cmp_gt_u32_e64 s[2:3], v134, v90
	v_add_u32_e32 v92, 0x4b, v107
	v_cmp_gt_u32_e32 vcc, 0x81, v92
	v_fmac_f32_e32 v194, 0x3e000000, v41
	s_and_b64 vcc, vcc, s[2:3]
	v_mul_f32_e32 v194, 0x3fb8aa3b, v194
	v_cndmask_b32_e32 v39, v93, v194, vcc
	v_add_u32_e32 v90, 0x50, v85
	v_cmp_gt_u32_e64 s[2:3], v134, v90
	v_add_u32_e32 v92, 0x50, v107
	v_cmp_gt_u32_e32 vcc, 0x81, v92
	v_fmac_f32_e32 v195, 0x3e000000, v42
	s_and_b64 vcc, vcc, s[2:3]
	v_mul_f32_e32 v195, 0x3fb8aa3b, v195
	v_cndmask_b32_e32 v41, v93, v195, vcc
	v_add_u32_e32 v90, 0x51, v85
	v_cmp_gt_u32_e64 s[2:3], v134, v90
	v_add_u32_e32 v92, 0x51, v107
	v_cmp_gt_u32_e32 vcc, 0x81, v92
	v_fmac_f32_e32 v196, 0x3e000000, v43
	s_and_b64 vcc, vcc, s[2:3]
	v_mul_f32_e32 v196, 0x3fb8aa3b, v196
	v_cndmask_b32_e32 v40, v93, v196, vcc
	v_add_u32_e32 v90, 0x52, v85
	v_cmp_gt_u32_e64 s[2:3], v134, v90
	v_add_u32_e32 v92, 0x52, v107
	v_cmp_gt_u32_e32 vcc, 0x81, v92
	v_fmac_f32_e32 v197, 0x3e000000, v44
	s_and_b64 vcc, vcc, s[2:3]
	v_mul_f32_e32 v197, 0x3fb8aa3b, v197
	v_cndmask_b32_e32 v43, v93, v197, vcc
	v_add_u32_e32 v90, 0x53, v85
	v_cmp_gt_u32_e64 s[2:3], v134, v90
	v_add_u32_e32 v92, 0x53, v107
	v_cmp_gt_u32_e32 vcc, 0x81, v92
	v_fmac_f32_e32 v198, 0x3e000000, v45
	s_and_b64 vcc, vcc, s[2:3]
	v_mul_f32_e32 v198, 0x3fb8aa3b, v198
	v_cndmask_b32_e32 v42, v93, v198, vcc
	v_add_u32_e32 v90, 0x58, v85
	v_cmp_gt_u32_e64 s[2:3], v134, v90
	v_add_u32_e32 v92, 0x58, v107
	v_cmp_gt_u32_e32 vcc, 0x81, v92
	v_fmac_f32_e32 v199, 0x3e000000, v46
	s_and_b64 vcc, vcc, s[2:3]
	v_mul_f32_e32 v199, 0x3fb8aa3b, v199
	v_cndmask_b32_e32 v45, v93, v199, vcc
	v_add_u32_e32 v90, 0x59, v85
	v_cmp_gt_u32_e64 s[2:3], v134, v90
	v_add_u32_e32 v92, 0x59, v107
	v_cmp_gt_u32_e32 vcc, 0x81, v92
	v_fmac_f32_e32 v200, 0x3e000000, v47
	s_and_b64 vcc, vcc, s[2:3]
	v_mul_f32_e32 v200, 0x3fb8aa3b, v200
	v_cndmask_b32_e32 v44, v93, v200, vcc
	v_add_u32_e32 v90, 0x5a, v85
	v_cmp_gt_u32_e64 s[2:3], v134, v90
	v_add_u32_e32 v92, 0x5a, v107
	v_cmp_gt_u32_e32 vcc, 0x81, v92
	v_fmac_f32_e32 v201, 0x3e000000, v48
	s_and_b64 vcc, vcc, s[2:3]
	v_mul_f32_e32 v201, 0x3fb8aa3b, v201
	v_cndmask_b32_e32 v47, v93, v201, vcc
	v_add_u32_e32 v90, 0x5b, v85
	v_cmp_gt_u32_e64 s[2:3], v134, v90
	v_add_u32_e32 v92, 0x5b, v107
	v_cmp_gt_u32_e32 vcc, 0x81, v92
	v_fmac_f32_e32 v202, 0x3e000000, v49
	s_and_b64 vcc, vcc, s[2:3]
	v_mul_f32_e32 v202, 0x3fb8aa3b, v202
	v_cndmask_b32_e32 v46, v93, v202, vcc
	v_add_u32_e32 v90, 0x60, v85
	v_cmp_gt_u32_e64 s[2:3], v134, v90
	v_add_u32_e32 v92, 0x60, v107
	v_cmp_gt_u32_e32 vcc, 0x81, v92
	v_fmac_f32_e32 v203, 0x3e000000, v18
	s_and_b64 vcc, vcc, s[2:3]
	v_mul_f32_e32 v203, 0x3fb8aa3b, v203
	v_cndmask_b32_e32 v49, v93, v203, vcc
	v_add_u32_e32 v90, 0x61, v85
	v_cmp_gt_u32_e64 s[2:3], v134, v90
	v_add_u32_e32 v92, 0x61, v107
	v_cmp_gt_u32_e32 vcc, 0x81, v92
	v_fmac_f32_e32 v204, 0x3e000000, v19
	s_and_b64 vcc, vcc, s[2:3]
	v_mul_f32_e32 v204, 0x3fb8aa3b, v204
	v_cndmask_b32_e32 v48, v93, v204, vcc
	v_add_u32_e32 v90, 0x62, v85
	v_cmp_gt_u32_e64 s[2:3], v134, v90
; DI int rowmap(int r, int lh) { return (r & 3) + 8 * (r >> 2) + 4 * lh; }
; DI void phase_mixb(const Prm& p, unsigned char* smem_raw, int S, int lgS, int& base) {
;     ...
;     float mx = -1e30f;
; #pragma unroll
;     for (int tt = 0; tt < 5; ++tt)
; #pragma unroll
;       for (int r = 0; r < 16; ++r) {
;         const int ik = i0 - 64 + 32 * tt + rowmap(r, lh);
;         const int rel = ik - qi;
;         const bool valid = (rel >= -64) && (rel <= 64) && (ik >= 0) && (ik < L);
;         const int bi = min(max(rel + 64, 0), 128);
;         const float s = valid ? (sc[tt][r] * 0.125f + bt[hd * 129 + bi]) * LOG2E : -1e30f;
;         sc[tt][r] = s;
;         mx = fmaxf(mx, s);
;       }
	v_add_u32_e32 v92, 0x62, v107
	v_cmp_gt_u32_e32 vcc, 0x81, v92
	v_fmac_f32_e32 v205, 0x3e000000, v20
	s_and_b64 vcc, vcc, s[2:3]
	v_mul_f32_e32 v205, 0x3fb8aa3b, v205
	v_cndmask_b32_e32 v19, v93, v205, vcc
	v_add_u32_e32 v90, 0x63, v85
	v_cmp_gt_u32_e64 s[2:3], v134, v90
	v_add_u32_e32 v92, 0x63, v107
	v_cmp_gt_u32_e32 vcc, 0x81, v92
	v_fmac_f32_e32 v206, 0x3e000000, v21
	s_and_b64 vcc, vcc, s[2:3]
	v_mul_f32_e32 v206, 0x3fb8aa3b, v206
	v_cndmask_b32_e32 v18, v93, v206, vcc
	v_add_u32_e32 v90, 0x68, v85
	v_cmp_gt_u32_e64 s[2:3], v134, v90
	v_add_u32_e32 v92, 0x68, v107
	v_cmp_gt_u32_e32 vcc, 0x81, v92
	v_fmac_f32_e32 v207, 0x3e000000, v22
	s_and_b64 vcc, vcc, s[2:3]
	v_mul_f32_e32 v207, 0x3fb8aa3b, v207
	v_cndmask_b32_e32 v21, v93, v207, vcc
	v_add_u32_e32 v90, 0x69, v85
	v_cmp_gt_u32_e64 s[2:3], v134, v90
	v_add_u32_e32 v92, 0x69, v107
	v_cmp_gt_u32_e32 vcc, 0x81, v92
	v_fmac_f32_e32 v208, 0x3e000000, v23
	s_and_b64 vcc, vcc, s[2:3]
	v_mul_f32_e32 v208, 0x3fb8aa3b, v208
	v_cndmask_b32_e32 v20, v93, v208, vcc
	v_add_u32_e32 v90, 0x6a, v85
	v_cmp_gt_u32_e64 s[2:3], v134, v90
	v_add_u32_e32 v92, 0x6a, v107
	v_cmp_gt_u32_e32 vcc, 0x81, v92
	v_fmac_f32_e32 v209, 0x3e000000, v24
	s_and_b64 vcc, vcc, s[2:3]
	v_mul_f32_e32 v209, 0x3fb8aa3b, v209
	v_cndmask_b32_e32 v23, v93, v209, vcc
	v_add_u32_e32 v90, 0x6b, v85
	v_cmp_gt_u32_e64 s[2:3], v134, v90
	v_add_u32_e32 v92, 0x6b, v107
	v_cmp_gt_u32_e32 vcc, 0x81, v92
	v_fmac_f32_e32 v210, 0x3e000000, v25
	s_and_b64 vcc, vcc, s[2:3]
	v_mul_f32_e32 v210, 0x3fb8aa3b, v210
	v_cndmask_b32_e32 v22, v93, v210, vcc
	v_add_u32_e32 v90, 0x70, v85
	v_cmp_gt_u32_e64 s[2:3], v134, v90
	v_add_u32_e32 v92, 0x70, v107
	v_cmp_gt_u32_e32 vcc, 0x81, v92
	v_fmac_f32_e32 v211, 0x3e000000, v26
	s_and_b64 vcc, vcc, s[2:3]
	v_mul_f32_e32 v211, 0x3fb8aa3b, v211
	v_cndmask_b32_e32 v25, v93, v211, vcc
	v_add_u32_e32 v90, 0x71, v85
	v_cmp_gt_u32_e64 s[2:3], v134, v90
	v_add_u32_e32 v92, 0x71, v107
	v_cmp_gt_u32_e32 vcc, 0x81, v92
	v_fmac_f32_e32 v212, 0x3e000000, v27
	s_and_b64 vcc, vcc, s[2:3]
	v_mul_f32_e32 v212, 0x3fb8aa3b, v212
	v_cndmask_b32_e32 v24, v93, v212, vcc
	v_add_u32_e32 v90, 0x72, v85
	v_cmp_gt_u32_e64 s[2:3], v134, v90
	v_add_u32_e32 v92, 0x72, v107
	v_cmp_gt_u32_e32 vcc, 0x81, v92
	v_fmac_f32_e32 v213, 0x3e000000, v28
	s_and_b64 vcc, vcc, s[2:3]
	v_mul_f32_e32 v213, 0x3fb8aa3b, v213
	v_cndmask_b32_e32 v27, v93, v213, vcc
	v_add_u32_e32 v90, 0x73, v85
	v_cmp_gt_u32_e64 s[2:3], v134, v90
	v_add_u32_e32 v92, 0x73, v107
	v_cmp_gt_u32_e32 vcc, 0x81, v92
	v_fmac_f32_e32 v214, 0x3e000000, v29
	s_and_b64 vcc, vcc, s[2:3]
	v_mul_f32_e32 v214, 0x3fb8aa3b, v214
	v_cndmask_b32_e32 v26, v93, v214, vcc
	v_add_u32_e32 v90, 0x78, v85
	v_cmp_gt_u32_e64 s[2:3], v134, v90
	v_add_u32_e32 v92, 0x78, v107
	v_cmp_gt_u32_e32 vcc, 0x81, v92
	v_fmac_f32_e32 v215, 0x3e000000, v30
	s_and_b64 vcc, vcc, s[2:3]
	v_mul_f32_e32 v215, 0x3fb8aa3b, v215
	v_cndmask_b32_e32 v29, v93, v215, vcc
	v_add_u32_e32 v90, 0x79, v85
	v_cmp_gt_u32_e64 s[2:3], v134, v90
	v_add_u32_e32 v92, 0x79, v107
	v_cmp_gt_u32_e32 vcc, 0x81, v92
	v_fmac_f32_e32 v216, 0x3e000000, v31
	s_and_b64 vcc, vcc, s[2:3]
	v_mul_f32_e32 v216, 0x3fb8aa3b, v216
	v_cndmask_b32_e32 v28, v93, v216, vcc
	v_add_u32_e32 v90, 0x7a, v85
	v_cmp_gt_u32_e64 s[2:3], v134, v90
	v_add_u32_e32 v92, 0x7a, v107
	v_cmp_gt_u32_e32 vcc, 0x81, v92
	v_fmac_f32_e32 v217, 0x3e000000, v32
	s_and_b64 vcc, vcc, s[2:3]
	v_mul_f32_e32 v217, 0x3fb8aa3b, v217
	v_cndmask_b32_e32 v31, v93, v217, vcc
	v_add_u32_e32 v90, 0x7b, v85
	v_cmp_gt_u32_e64 s[2:3], v134, v90
	v_add_u32_e32 v92, 0x7b, v107
	v_cmp_gt_u32_e32 vcc, 0x81, v92
	v_fmac_f32_e32 v218, 0x3e000000, v33
	s_and_b64 vcc, vcc, s[2:3]
	v_mul_f32_e32 v218, 0x3fb8aa3b, v218
	v_cndmask_b32_e32 v30, v93, v218, vcc
	v_add_u32_e32 v90, 0x80, v85
	v_cmp_gt_u32_e64 s[2:3], v134, v90
	v_add_u32_e32 v92, 0x80, v107
	v_cmp_gt_u32_e32 vcc, 0x81, v92
	v_fmac_f32_e32 v219, 0x3e000000, v2
	s_and_b64 vcc, vcc, s[2:3]
	v_mul_f32_e32 v219, 0x3fb8aa3b, v219
	v_cndmask_b32_e32 v33, v93, v219, vcc
	v_add_u32_e32 v90, 0x81, v85
	v_cmp_gt_u32_e64 s[2:3], v134, v90
	v_add_u32_e32 v92, 0x81, v107
	v_cmp_gt_u32_e32 vcc, 0x81, v92
	v_fmac_f32_e32 v220, 0x3e000000, v3
	s_and_b64 vcc, vcc, s[2:3]
	v_mul_f32_e32 v220, 0x3fb8aa3b, v220
	v_cndmask_b32_e32 v32, v93, v220, vcc
	v_add_u32_e32 v90, 0x82, v85
	v_cmp_gt_u32_e64 s[2:3], v134, v90
	v_add_u32_e32 v92, 0x82, v107
	v_cmp_gt_u32_e32 vcc, 0x81, v92
	v_fmac_f32_e32 v221, 0x3e000000, v4
	s_and_b64 vcc, vcc, s[2:3]
	v_mul_f32_e32 v221, 0x3fb8aa3b, v221
	v_cndmask_b32_e32 v156, v93, v221, vcc
	v_add_u32_e32 v90, 0x83, v85
	v_cmp_gt_u32_e64 s[2:3], v134, v90
	v_add_u32_e32 v92, 0x83, v107
	v_cmp_gt_u32_e32 vcc, 0x81, v92
	v_fmac_f32_e32 v222, 0x3e000000, v5
	s_and_b64 vcc, vcc, s[2:3]
	v_mul_f32_e32 v222, 0x3fb8aa3b, v222
	v_cndmask_b32_e32 v91, v93, v222, vcc
	v_add_u32_e32 v90, 0x88, v85
	v_cmp_gt_u32_e64 s[2:3], v134, v90
	v_add_u32_e32 v92, 0x88, v107
	v_cmp_gt_u32_e32 vcc, 0x81, v92
	v_fmac_f32_e32 v223, 0x3e000000, v6
	s_and_b64 vcc, vcc, s[2:3]
	v_mul_f32_e32 v223, 0x3fb8aa3b, v223
	v_cndmask_b32_e32 v158, v93, v223, vcc
	v_add_u32_e32 v90, 0x89, v85
	v_cmp_gt_u32_e64 s[2:3], v134, v90
	v_add_u32_e32 v92, 0x89, v107
	v_cmp_gt_u32_e32 vcc, 0x81, v92
	v_fmac_f32_e32 v226, 0x3e000000, v7
	s_and_b64 vcc, vcc, s[2:3]
	v_mul_f32_e32 v226, 0x3fb8aa3b, v226
	v_cndmask_b32_e32 v157, v93, v226, vcc
	v_add_u32_e32 v90, 0x8a, v85
	v_cmp_gt_u32_e64 s[2:3], v134, v90
	v_add_u32_e32 v92, 0x8a, v107
	v_cmp_gt_u32_e32 vcc, 0x81, v92
	v_fmac_f32_e32 v227, 0x3e000000, v8
	s_and_b64 vcc, vcc, s[2:3]
	v_mul_f32_e32 v227, 0x3fb8aa3b, v227
; DI int rowmap(int r, int lh) { return (r & 3) + 8 * (r >> 2) + 4 * lh; }
; DI float ex2(float x) { return __builtin_amdgcn_exp2f(x); }
; DI void phase_mixb(const Prm& p, unsigned char* smem_raw, int S, int lgS, int& base) {
;     ...
;     float mx = -1e30f;
; #pragma unroll
;     for (int tt = 0; tt < 5; ++tt)
; #pragma unroll
;       for (int r = 0; r < 16; ++r) {
;         const int ik = i0 - 64 + 32 * tt + rowmap(r, lh);
;         const int rel = ik - qi;
;         const bool valid = (rel >= -64) && (rel <= 64) && (ik >= 0) && (ik < L);
;         const int bi = min(max(rel + 64, 0), 128);
;         const float s = valid ? (sc[tt][r] * 0.125f + bt[hd * 129 + bi]) * LOG2E : -1e30f;
;         sc[tt][r] = s;
;         mx = fmaxf(mx, s);
;       }
;     mx = fmaxf(mx, __shfl_xor(mx, 32));
;     float sum = 0.f;
; #pragma unroll
;     for (int tt = 0; tt < 5; ++tt)
; #pragma unroll
;       for (int r = 0; r < 16; ++r) {
;         const float pv = ex2(sc[tt][r] - mx);
;         sum += pv;
;         sc[tt][r] = pv;
;       }
;     sum += __shfl_xor(sum, 32);
	v_cndmask_b32_e32 v160, v93, v227, vcc
	v_add_u32_e32 v90, 0x8b, v85
	v_cmp_gt_u32_e64 s[2:3], v134, v90
	v_add_u32_e32 v92, 0x8b, v107
	v_cmp_gt_u32_e32 vcc, 0x81, v92
	v_fmac_f32_e32 v228, 0x3e000000, v9
	s_and_b64 vcc, vcc, s[2:3]
	v_mul_f32_e32 v228, 0x3fb8aa3b, v228
	v_cndmask_b32_e32 v159, v93, v228, vcc
	v_add_u32_e32 v90, 0x90, v85
	v_cmp_gt_u32_e64 s[2:3], v134, v90
	v_add_u32_e32 v92, 0x90, v107
	v_cmp_gt_u32_e32 vcc, 0x81, v92
	v_fmac_f32_e32 v229, 0x3e000000, v10
	s_and_b64 vcc, vcc, s[2:3]
	v_mul_f32_e32 v229, 0x3fb8aa3b, v229
	v_cndmask_b32_e32 v162, v93, v229, vcc
	v_add_u32_e32 v90, 0x91, v85
	v_cmp_gt_u32_e64 s[2:3], v134, v90
	v_add_u32_e32 v92, 0x91, v107
	v_cmp_gt_u32_e32 vcc, 0x81, v92
	v_fmac_f32_e32 v234, 0x3e000000, v11
	s_and_b64 vcc, vcc, s[2:3]
	v_mul_f32_e32 v234, 0x3fb8aa3b, v234
	v_cndmask_b32_e32 v161, v93, v234, vcc
	v_add_u32_e32 v90, 0x92, v85
	v_cmp_gt_u32_e64 s[2:3], v134, v90
	v_add_u32_e32 v92, 0x92, v107
	v_cmp_gt_u32_e32 vcc, 0x81, v92
	v_fmac_f32_e32 v235, 0x3e000000, v12
	s_and_b64 vcc, vcc, s[2:3]
	v_mul_f32_e32 v235, 0x3fb8aa3b, v235
	v_cndmask_b32_e32 v11, v93, v235, vcc
	v_add_u32_e32 v90, 0x93, v85
	v_cmp_gt_u32_e64 s[2:3], v134, v90
	v_add_u32_e32 v92, 0x93, v107
	v_cmp_gt_u32_e32 vcc, 0x81, v92
	v_fmac_f32_e32 v236, 0x3e000000, v13
	s_and_b64 vcc, vcc, s[2:3]
	v_mul_f32_e32 v236, 0x3fb8aa3b, v236
	v_cndmask_b32_e32 v10, v93, v236, vcc
	v_add_u32_e32 v90, 0x98, v85
	v_cmp_gt_u32_e64 s[2:3], v134, v90
	v_add_u32_e32 v92, 0x98, v107
	v_cmp_gt_u32_e32 vcc, 0x81, v92
	v_fmac_f32_e32 v237, 0x3e000000, v14
	s_and_b64 vcc, vcc, s[2:3]
	v_mul_f32_e32 v237, 0x3fb8aa3b, v237
	v_cndmask_b32_e32 v13, v93, v237, vcc
	v_add_u32_e32 v90, 0x99, v85
	v_cmp_gt_u32_e64 s[2:3], v134, v90
	v_add_u32_e32 v92, 0x99, v107
	v_cmp_gt_u32_e32 vcc, 0x81, v92
	v_fmac_f32_e32 v244, 0x3e000000, v15
	s_and_b64 vcc, vcc, s[2:3]
	v_mul_f32_e32 v244, 0x3fb8aa3b, v244
	v_cndmask_b32_e32 v12, v93, v244, vcc
	v_add_u32_e32 v90, 0x9a, v85
	v_cmp_gt_u32_e64 s[2:3], v134, v90
	v_add_u32_e32 v92, 0x9a, v107
	v_cmp_gt_u32_e32 vcc, 0x81, v92
	v_fmac_f32_e32 v245, 0x3e000000, v16
	s_and_b64 vcc, vcc, s[2:3]
	v_mul_f32_e32 v245, 0x3fb8aa3b, v245
	v_cndmask_b32_e32 v15, v93, v245, vcc
	v_add_u32_e32 v90, 0x9b, v85
	v_cmp_gt_u32_e64 s[2:3], v134, v90
	v_add_u32_e32 v92, 0x9b, v107
	v_cmp_gt_u32_e32 vcc, 0x81, v92
	v_fmac_f32_e32 v246, 0x3e000000, v17
	s_and_b64 vcc, vcc, s[2:3]
	v_mul_f32_e32 v246, 0x3fb8aa3b, v246
	v_cndmask_b32_e32 v14, v93, v246, vcc
	v_subrev_u32_e32 v82, 64, v133
	v_subrev_u32_e32 v66, 32, v133
	v_add_u32_e32 v38, 32, v133
	v_add_u32_e32 v37, 64, v133
	s_mov_b32 s2, 0xf149f2ca
	v_max3_f32 v2, v84, s2, v83
	v_max3_f32 v2, v2, v86, v67
	v_max3_f32 v2, v2, v69, v68
	v_max3_f32 v2, v2, v71, v70
	v_max3_f32 v2, v2, v73, v72
	v_max3_f32 v2, v2, v75, v74
	v_max3_f32 v2, v2, v77, v76
	v_max3_f32 v2, v2, v79, v78
	v_max3_f32 v2, v2, v81, v80
	v_max3_f32 v2, v2, v51, v50
	v_max3_f32 v2, v2, v53, v52
	v_max3_f32 v2, v2, v55, v54
	v_max3_f32 v2, v2, v57, v56
	v_max3_f32 v2, v2, v59, v58
	v_max3_f32 v2, v2, v61, v60
	v_max3_f32 v2, v2, v63, v62
	v_max3_f32 v2, v2, v65, v64
	v_max3_f32 v2, v2, v35, v34
	v_max3_f32 v2, v2, v87, v88
	v_max3_f32 v2, v2, v89, v39
	v_max3_f32 v2, v2, v41, v40
	v_max3_f32 v2, v2, v43, v42
	v_max3_f32 v2, v2, v45, v44
	v_max3_f32 v2, v2, v47, v46
	v_max3_f32 v2, v2, v49, v48
	v_max3_f32 v2, v2, v19, v18
	v_max3_f32 v2, v2, v21, v20
	v_max3_f32 v2, v2, v23, v22
	v_max3_f32 v2, v2, v25, v24
	v_max3_f32 v2, v2, v27, v26
	v_max3_f32 v2, v2, v29, v28
	v_max3_f32 v2, v2, v31, v30
	v_max3_f32 v2, v2, v33, v32
	v_max3_f32 v2, v2, v156, v91
	v_max3_f32 v2, v2, v158, v157
	v_max3_f32 v2, v2, v160, v159
	v_max3_f32 v2, v2, v162, v161
	v_max3_f32 v2, v2, v11, v10
	v_max3_f32 v2, v2, v13, v12
	v_max3_f32 v2, v2, v15, v14
	ds_bpermute_b32 v3, v106, v2
	v_readlane_b32 s36, v253, 24
	v_readlane_b32 s38, v253, 26
	v_readlane_b32 s39, v253, 27
	s_movk_i32 s4, 0x900
	s_waitcnt lgkmcnt(0)
	v_max_f32_e32 v3, v3, v3
	v_max_f32_e32 v36, v2, v3
	v_sub_f32_e32 v2, v84, v36
	v_exp_f32_e32 v2, v2
	v_sub_f32_e32 v3, v83, v36
	v_exp_f32_e32 v3, v3
	v_sub_f32_e32 v17, v73, v36
	v_add_f32_e32 v4, 0, v2
	v_exp_f32_e32 v148, v17
	v_add_f32_e32 v5, v3, v4
	v_sub_f32_e32 v4, v86, v36
	v_exp_f32_e32 v4, v4
	v_sub_f32_e32 v17, v72, v36
	v_exp_f32_e32 v149, v17
	v_sub_f32_e32 v17, v75, v36
	v_add_f32_e32 v6, v4, v5
	v_sub_f32_e32 v5, v67, v36
	v_exp_f32_e32 v5, v5
	v_exp_f32_e32 v150, v17
	v_sub_f32_e32 v17, v74, v36
	v_exp_f32_e32 v151, v17
	v_add_f32_e32 v7, v5, v6
	v_sub_f32_e32 v6, v69, v36
	v_exp_f32_e32 v6, v6
	v_sub_f32_e32 v17, v77, v36
	v_exp_f32_e32 v152, v17
	v_sub_f32_e32 v17, v76, v36
	v_add_f32_e32 v8, v6, v7
	v_sub_f32_e32 v7, v68, v36
	v_exp_f32_e32 v7, v7
	v_exp_f32_e32 v153, v17
	v_sub_f32_e32 v17, v79, v36
	v_exp_f32_e32 v154, v17
	v_add_f32_e32 v9, v7, v8
	v_sub_f32_e32 v8, v71, v36
	v_exp_f32_e32 v8, v8
	v_sub_f32_e32 v17, v78, v36
	v_exp_f32_e32 v155, v17
	v_sub_f32_e32 v17, v81, v36
	v_add_f32_e32 v16, v8, v9
	v_sub_f32_e32 v9, v70, v36
	v_exp_f32_e32 v9, v9
	v_exp_f32_e32 v137, v17
	v_sub_f32_e32 v17, v80, v36
	v_exp_f32_e32 v140, v17
	v_add_f32_e32 v16, v9, v16
	v_add_f32_e32 v16, v148, v16
	v_add_f32_e32 v16, v149, v16
	v_add_f32_e32 v16, v150, v16
	v_add_f32_e32 v16, v151, v16
	v_add_f32_e32 v16, v152, v16
	v_add_f32_e32 v16, v153, v16
	v_sub_f32_e32 v17, v51, v36
	v_add_f32_e32 v16, v154, v16
	v_exp_f32_e32 v141, v17
	v_sub_f32_e32 v17, v50, v36
	v_add_f32_e32 v16, v155, v16
	v_exp_f32_e32 v143, v17
	v_sub_f32_e32 v17, v53, v36
	v_add_f32_e32 v16, v137, v16
	v_exp_f32_e32 v144, v17
	v_sub_f32_e32 v17, v52, v36
; DI f32x16 zero16() { f32x16 z; for (int i = 0; i < 16; ++i) z[i] = 0.f; return z; }
; DI float ex2(float x) { return __builtin_amdgcn_exp2f(x); }
; DI void phase_mixb(const Prm& p, unsigned char* smem_raw, int S, int lgS, int& base) {
;     ...
;     float sum = 0.f;
; #pragma unroll
;     for (int tt = 0; tt < 5; ++tt)
; #pragma unroll
;       for (int r = 0; r < 16; ++r) {
;         const float pv = ex2(sc[tt][r] - mx);
;         sum += pv;
;         sc[tt][r] = pv;
;       }
;     sum += __shfl_xor(sum, 32);
;     f32x16 oacc[2];
;     oacc[0] = zero16(); oacc[1] = zero16();
; #pragma unroll
;     for (int tt = 0; tt < 5; ++tt) {
; #pragma unroll
;       for (int e = 0; e < 4; ++e) {
;         const int c = lane + 64 * e, key = c >> 3, dch = c & 7;
;         int ik = i0 - 64 + 32 * tt + key;
;         ik = min(max(ik, 0), L - 1);
;         const u32x4 raw = *(const u32x4*)(p.bqkv + (size_t)(tokbase + (ik << lgd)) * 1152 + 768 + hc + dch * 8);
	v_add_f32_e32 v16, v140, v16
	v_exp_f32_e32 v145, v17
	v_sub_f32_e32 v17, v55, v36
	v_add_f32_e32 v16, v141, v16
	v_exp_f32_e32 v146, v17
	v_sub_f32_e32 v17, v54, v36
	v_add_f32_e32 v16, v143, v16
	v_exp_f32_e32 v147, v17
	v_sub_f32_e32 v17, v57, v36
	v_add_f32_e32 v16, v144, v16
	v_exp_f32_e32 v92, v17
	v_sub_f32_e32 v17, v56, v36
	v_add_f32_e32 v16, v145, v16
	v_exp_f32_e32 v93, v17
	v_sub_f32_e32 v17, v59, v36
	v_add_f32_e32 v16, v146, v16
	v_exp_f32_e32 v134, v17
	v_sub_f32_e32 v17, v58, v36
	v_add_f32_e32 v16, v147, v16
	v_exp_f32_e32 v135, v17
	v_sub_f32_e32 v17, v61, v36
	v_add_f32_e32 v16, v92, v16
	v_exp_f32_e32 v136, v17
	v_sub_f32_e32 v17, v60, v36
	v_add_f32_e32 v16, v93, v16
	v_exp_f32_e32 v138, v17
	v_sub_f32_e32 v17, v63, v36
	v_add_f32_e32 v16, v134, v16
	v_exp_f32_e32 v139, v17
	v_sub_f32_e32 v17, v62, v36
	v_add_f32_e32 v16, v135, v16
	v_exp_f32_e32 v142, v17
	v_sub_f32_e32 v17, v65, v36
	v_add_f32_e32 v16, v136, v16
	v_exp_f32_e32 v79, v17
	v_sub_f32_e32 v17, v64, v36
	v_add_f32_e32 v16, v138, v16
	v_exp_f32_e32 v83, v17
	v_sub_f32_e32 v17, v35, v36
	v_add_f32_e32 v16, v139, v16
	v_exp_f32_e32 v84, v17
	v_sub_f32_e32 v17, v34, v36
	v_add_f32_e32 v16, v142, v16
	v_exp_f32_e32 v86, v17
	v_sub_f32_e32 v17, v87, v36
	v_add_f32_e32 v16, v79, v16
	v_exp_f32_e32 v87, v17
	v_sub_f32_e32 v17, v88, v36
	v_add_f32_e32 v16, v83, v16
	v_exp_f32_e32 v88, v17
	v_sub_f32_e32 v17, v89, v36
	v_add_f32_e32 v16, v84, v16
	v_exp_f32_e32 v89, v17
	v_sub_f32_e32 v17, v39, v36
	v_add_f32_e32 v16, v86, v16
	v_exp_f32_e32 v90, v17
	v_sub_f32_e32 v17, v41, v36
	v_add_f32_e32 v16, v87, v16
	v_exp_f32_e32 v74, v17
	v_sub_f32_e32 v17, v40, v36
	v_add_f32_e32 v16, v88, v16
	v_exp_f32_e32 v75, v17
	v_sub_f32_e32 v17, v43, v36
	v_add_f32_e32 v16, v89, v16
	v_exp_f32_e32 v76, v17
	v_sub_f32_e32 v17, v42, v36
	v_add_f32_e32 v16, v90, v16
	v_exp_f32_e32 v77, v17
	v_sub_f32_e32 v17, v45, v36
	v_add_f32_e32 v16, v74, v16
	v_exp_f32_e32 v78, v17
	v_sub_f32_e32 v17, v44, v36
	v_add_f32_e32 v16, v75, v16
	v_exp_f32_e32 v80, v17
	v_sub_f32_e32 v17, v47, v36
	v_add_f32_e32 v16, v76, v16
	v_exp_f32_e32 v81, v17
	v_sub_f32_e32 v17, v46, v36
	v_add_f32_e32 v16, v77, v16
	v_exp_f32_e32 v85, v17
	v_sub_f32_e32 v17, v49, v36
	v_add_f32_e32 v16, v78, v16
	v_exp_f32_e32 v62, v17
	v_sub_f32_e32 v17, v48, v36
	v_add_f32_e32 v16, v80, v16
	v_exp_f32_e32 v65, v17
	v_sub_f32_e32 v17, v19, v36
	v_add_f32_e32 v16, v81, v16
	v_exp_f32_e32 v67, v17
	v_sub_f32_e32 v17, v18, v36
	v_add_f32_e32 v16, v85, v16
	v_exp_f32_e32 v69, v17
	v_sub_f32_e32 v17, v21, v36
	v_add_f32_e32 v16, v62, v16
	v_exp_f32_e32 v70, v17
	v_sub_f32_e32 v17, v20, v36
	v_add_f32_e32 v16, v65, v16
	v_exp_f32_e32 v71, v17
	v_sub_f32_e32 v17, v23, v36
	v_add_f32_e32 v16, v67, v16
	v_exp_f32_e32 v72, v17
	v_sub_f32_e32 v17, v22, v36
	v_add_f32_e32 v16, v69, v16
	v_exp_f32_e32 v73, v17
	v_sub_f32_e32 v17, v25, v36
	v_add_f32_e32 v16, v70, v16
	v_exp_f32_e32 v57, v17
	v_sub_f32_e32 v17, v24, v36
	v_add_f32_e32 v16, v71, v16
	v_exp_f32_e32 v58, v17
	v_sub_f32_e32 v17, v27, v36
	v_add_f32_e32 v16, v72, v16
	v_exp_f32_e32 v59, v17
	v_sub_f32_e32 v17, v26, v36
	v_add_f32_e32 v16, v73, v16
	v_exp_f32_e32 v60, v17
	v_sub_f32_e32 v17, v29, v36
	v_add_f32_e32 v16, v57, v16
	v_exp_f32_e32 v61, v17
	v_sub_f32_e32 v17, v28, v36
	v_add_f32_e32 v16, v58, v16
	v_exp_f32_e32 v63, v17
	v_sub_f32_e32 v17, v31, v36
	v_add_f32_e32 v16, v59, v16
	v_exp_f32_e32 v64, v17
	v_sub_f32_e32 v17, v30, v36
	v_add_f32_e32 v16, v60, v16
	v_exp_f32_e32 v68, v17
	v_sub_f32_e32 v17, v33, v36
	v_add_f32_e32 v16, v61, v16
	v_exp_f32_e32 v49, v17
	v_sub_f32_e32 v17, v32, v36
	v_add_f32_e32 v16, v63, v16
	v_exp_f32_e32 v50, v17
	v_sub_f32_e32 v17, v156, v36
	v_add_f32_e32 v16, v64, v16
	v_exp_f32_e32 v51, v17
	v_sub_f32_e32 v17, v91, v36
	v_add_f32_e32 v16, v68, v16
	v_exp_f32_e32 v52, v17
	v_sub_f32_e32 v17, v158, v36
	v_add_f32_e32 v16, v49, v16
	v_exp_f32_e32 v53, v17
	v_sub_f32_e32 v17, v157, v36
	v_add_f32_e32 v16, v50, v16
	v_exp_f32_e32 v54, v17
	v_sub_f32_e32 v17, v160, v36
	v_add_f32_e32 v16, v51, v16
	v_exp_f32_e32 v55, v17
	v_sub_f32_e32 v17, v159, v36
	v_add_f32_e32 v16, v52, v16
	v_exp_f32_e32 v56, v17
	v_sub_f32_e32 v17, v162, v36
	v_add_f32_e32 v16, v53, v16
	v_exp_f32_e32 v41, v17
	v_sub_f32_e32 v17, v161, v36
	v_add_f32_e32 v16, v54, v16
	v_exp_f32_e32 v42, v17
	v_sub_f32_e32 v11, v11, v36
	v_add_f32_e32 v16, v55, v16
	v_exp_f32_e32 v43, v11
	v_sub_f32_e32 v10, v10, v36
	v_add_f32_e32 v16, v56, v16
	v_exp_f32_e32 v44, v10
	v_add_f32_e32 v16, v41, v16
	v_add_f32_e32 v16, v42, v16
	v_add_f32_e32 v11, v43, v16
	v_add_f32_e32 v10, v44, v11
	v_sub_f32_e32 v11, v13, v36
	v_exp_f32_e32 v45, v11
	v_sub_f32_e32 v11, v12, v36
	v_exp_f32_e32 v46, v11
	v_sub_f32_e32 v11, v15, v36
	v_exp_f32_e32 v47, v11
	v_sub_f32_e32 v11, v14, v36
	v_exp_f32_e32 v48, v11
	v_add_f32_e32 v10, v45, v10
	v_add_f32_e32 v10, v46, v10
	v_add_f32_e32 v10, v47, v10
	v_add_f32_e32 v39, v48, v10
	v_mov_b64_e32 v[156:157], s[38:39]
	v_mov_b32_e32 v158, v96
	v_mov_b32_e32 v159, v1
	v_or_b32_e32 v40, v82, v108
	v_max_i32_e32 v40, 0, v40
	v_min_i32_e32 v40, v40, v132
	v_lshl_add_u32 v40, v40, v99, v131
	v_mad_i64_i32 v[14:15], s[2:3], v40, s4, v[156:157]
	v_lshl_add_u64 v[14:15], v[14:15], 0, v[102:103]
	v_lshl_add_u64 v[14:15], v[14:15], 0, v[158:159]
	global_load_dwordx4 v[160:163], v[14:15], off offset:1536
	v_or_b32_e32 v40, v82, v110
	v_max_i32_e32 v40, 0, v40
	v_min_i32_e32 v40, v40, v132
	v_lshl_add_u32 v40, v40, v99, v131
	v_mad_i64_i32 v[14:15], s[2:3], v40, s4, v[156:157]
	v_lshl_add_u64 v[14:15], v[14:15], 0, v[102:103]
	v_lshl_add_u64 v[14:15], v[14:15], 0, v[158:159]
; DI void phase_mixb(const Prm& p, unsigned char* smem_raw, int S, int lgS, int& base) {
;     ...
;     for (int tt = 0; tt < 5; ++tt) {
; #pragma unroll
;       for (int e = 0; e < 4; ++e) {
;         const int c = lane + 64 * e, key = c >> 3, dch = c & 7;
;         int ik = i0 - 64 + 32 * tt + key;
;         ik = min(max(ik, 0), L - 1);
;         const u32x4 raw = *(const u32x4*)(p.bqkv + (size_t)(tokbase + (ik << lgd)) * 1152 + 768 + hc + dch * 8);
	global_load_dwordx4 v[164:167], v[14:15], off offset:1536
	v_or_b32_e32 v40, v82, v111
	v_max_i32_e32 v40, 0, v40
	v_min_i32_e32 v40, v40, v132
	v_lshl_add_u32 v40, v40, v99, v131
	v_mad_i64_i32 v[14:15], s[2:3], v40, s4, v[156:157]
	v_lshl_add_u64 v[14:15], v[14:15], 0, v[102:103]
	v_lshl_add_u64 v[14:15], v[14:15], 0, v[158:159]
	global_load_dwordx4 v[168:171], v[14:15], off offset:1536
	v_or_b32_e32 v40, v82, v112
	v_max_i32_e32 v40, 0, v40
	v_min_i32_e32 v40, v40, v132
	v_lshl_add_u32 v40, v40, v99, v131
	v_mad_i64_i32 v[14:15], s[2:3], v40, s4, v[156:157]
	v_lshl_add_u64 v[14:15], v[14:15], 0, v[102:103]
	v_lshl_add_u64 v[14:15], v[14:15], 0, v[158:159]
	global_load_dwordx4 v[172:175], v[14:15], off offset:1536
	v_or_b32_e32 v40, v66, v108
	v_max_i32_e32 v40, 0, v40
	v_min_i32_e32 v40, v40, v132
	v_lshl_add_u32 v40, v40, v99, v131
	v_mad_i64_i32 v[14:15], s[2:3], v40, s4, v[156:157]
	v_lshl_add_u64 v[14:15], v[14:15], 0, v[102:103]
	v_lshl_add_u64 v[14:15], v[14:15], 0, v[158:159]
	global_load_dwordx4 v[176:179], v[14:15], off offset:1536
	v_or_b32_e32 v40, v66, v110
	v_max_i32_e32 v40, 0, v40
	v_min_i32_e32 v40, v40, v132
	v_lshl_add_u32 v40, v40, v99, v131
	v_mad_i64_i32 v[14:15], s[2:3], v40, s4, v[156:157]
	v_lshl_add_u64 v[14:15], v[14:15], 0, v[102:103]
	v_lshl_add_u64 v[14:15], v[14:15], 0, v[158:159]
	global_load_dwordx4 v[180:183], v[14:15], off offset:1536
	v_or_b32_e32 v40, v66, v111
	v_max_i32_e32 v40, 0, v40
	v_min_i32_e32 v40, v40, v132
	v_lshl_add_u32 v40, v40, v99, v131
	v_mad_i64_i32 v[14:15], s[2:3], v40, s4, v[156:157]
	v_lshl_add_u64 v[14:15], v[14:15], 0, v[102:103]
	v_lshl_add_u64 v[14:15], v[14:15], 0, v[158:159]
	global_load_dwordx4 v[184:187], v[14:15], off offset:1536
	v_or_b32_e32 v40, v66, v112
	v_max_i32_e32 v40, 0, v40
	v_min_i32_e32 v40, v40, v132
	v_lshl_add_u32 v40, v40, v99, v131
	v_mad_i64_i32 v[14:15], s[2:3], v40, s4, v[156:157]
	v_lshl_add_u64 v[14:15], v[14:15], 0, v[102:103]
	v_lshl_add_u64 v[14:15], v[14:15], 0, v[158:159]
	global_load_dwordx4 v[188:191], v[14:15], off offset:1536
	v_or_b32_e32 v40, v133, v108
	v_max_i32_e32 v40, 0, v40
	v_min_i32_e32 v40, v40, v132
	v_lshl_add_u32 v40, v40, v99, v131
	v_mad_i64_i32 v[14:15], s[2:3], v40, s4, v[156:157]
	v_lshl_add_u64 v[14:15], v[14:15], 0, v[102:103]
	v_lshl_add_u64 v[14:15], v[14:15], 0, v[158:159]
	global_load_dwordx4 v[192:195], v[14:15], off offset:1536
	v_or_b32_e32 v40, v133, v110
	v_max_i32_e32 v40, 0, v40
	v_min_i32_e32 v40, v40, v132
	v_lshl_add_u32 v40, v40, v99, v131
	v_mad_i64_i32 v[14:15], s[2:3], v40, s4, v[156:157]
	v_lshl_add_u64 v[14:15], v[14:15], 0, v[102:103]
	v_lshl_add_u64 v[14:15], v[14:15], 0, v[158:159]
	global_load_dwordx4 v[196:199], v[14:15], off offset:1536
	v_or_b32_e32 v40, v133, v111
	v_max_i32_e32 v40, 0, v40
	v_min_i32_e32 v40, v40, v132
	v_lshl_add_u32 v40, v40, v99, v131
	v_mad_i64_i32 v[14:15], s[2:3], v40, s4, v[156:157]
	v_lshl_add_u64 v[14:15], v[14:15], 0, v[102:103]
	v_lshl_add_u64 v[14:15], v[14:15], 0, v[158:159]
	global_load_dwordx4 v[200:203], v[14:15], off offset:1536
	v_or_b32_e32 v40, v133, v112
	v_max_i32_e32 v40, 0, v40
	v_min_i32_e32 v40, v40, v132
	v_lshl_add_u32 v40, v40, v99, v131
	v_mad_i64_i32 v[14:15], s[2:3], v40, s4, v[156:157]
	v_lshl_add_u64 v[14:15], v[14:15], 0, v[102:103]
	v_lshl_add_u64 v[14:15], v[14:15], 0, v[158:159]
	global_load_dwordx4 v[204:207], v[14:15], off offset:1536
	v_or_b32_e32 v40, v38, v108
	v_max_i32_e32 v40, 0, v40
	v_min_i32_e32 v40, v40, v132
	v_lshl_add_u32 v40, v40, v99, v131
	v_mad_i64_i32 v[14:15], s[2:3], v40, s4, v[156:157]
	v_lshl_add_u64 v[14:15], v[14:15], 0, v[102:103]
	v_lshl_add_u64 v[14:15], v[14:15], 0, v[158:159]
	global_load_dwordx4 v[208:211], v[14:15], off offset:1536
	v_or_b32_e32 v40, v38, v110
	v_max_i32_e32 v40, 0, v40
	v_min_i32_e32 v40, v40, v132
	v_lshl_add_u32 v40, v40, v99, v131
	v_mad_i64_i32 v[14:15], s[2:3], v40, s4, v[156:157]
	v_lshl_add_u64 v[14:15], v[14:15], 0, v[102:103]
	v_lshl_add_u64 v[14:15], v[14:15], 0, v[158:159]
	global_load_dwordx4 v[212:215], v[14:15], off offset:1536
	v_or_b32_e32 v40, v38, v111
	v_max_i32_e32 v40, 0, v40
	v_min_i32_e32 v40, v40, v132
	v_lshl_add_u32 v40, v40, v99, v131
	v_mad_i64_i32 v[14:15], s[2:3], v40, s4, v[156:157]
	v_lshl_add_u64 v[14:15], v[14:15], 0, v[102:103]
	v_lshl_add_u64 v[14:15], v[14:15], 0, v[158:159]
	global_load_dwordx4 v[216:219], v[14:15], off offset:1536
	v_or_b32_e32 v40, v38, v112
	v_max_i32_e32 v40, 0, v40
	v_min_i32_e32 v40, v40, v132
	v_lshl_add_u32 v40, v40, v99, v131
	v_mad_i64_i32 v[14:15], s[2:3], v40, s4, v[156:157]
	v_lshl_add_u64 v[14:15], v[14:15], 0, v[102:103]
	v_lshl_add_u64 v[14:15], v[14:15], 0, v[158:159]
	global_load_dwordx4 v[220:223], v[14:15], off offset:1536
	v_or_b32_e32 v40, v37, v108
	v_max_i32_e32 v40, 0, v40
	v_min_i32_e32 v40, v40, v132
	v_lshl_add_u32 v40, v40, v99, v131
	v_mad_i64_i32 v[14:15], s[2:3], v40, s4, v[156:157]
	v_lshl_add_u64 v[14:15], v[14:15], 0, v[102:103]
	v_lshl_add_u64 v[14:15], v[14:15], 0, v[158:159]
	global_load_dwordx4 v[226:229], v[14:15], off offset:1536
	v_or_b32_e32 v40, v37, v110
	v_max_i32_e32 v40, 0, v40
	v_min_i32_e32 v40, v40, v132
	v_lshl_add_u32 v40, v40, v99, v131
	v_mad_i64_i32 v[14:15], s[2:3], v40, s4, v[156:157]
	v_lshl_add_u64 v[14:15], v[14:15], 0, v[102:103]
	v_lshl_add_u64 v[14:15], v[14:15], 0, v[158:159]
	global_load_dwordx4 v[234:237], v[14:15], off offset:1536
	v_or_b32_e32 v40, v37, v111
	v_max_i32_e32 v40, 0, v40
	v_min_i32_e32 v40, v40, v132
	v_lshl_add_u32 v40, v40, v99, v131
	v_mad_i64_i32 v[14:15], s[2:3], v40, s4, v[156:157]
	v_lshl_add_u64 v[14:15], v[14:15], 0, v[102:103]
	v_lshl_add_u64 v[14:15], v[14:15], 0, v[158:159]
	global_load_dwordx4 v[244:247], v[14:15], off offset:1536
	v_or_b32_e32 v40, v37, v112
	v_max_i32_e32 v40, 0, v40
	v_min_i32_e32 v40, v40, v132
	v_lshl_add_u32 v40, v40, v99, v131
	v_mad_i64_i32 v[14:15], s[2:3], v40, s4, v[156:157]
	v_lshl_add_u64 v[14:15], v[14:15], 0, v[102:103]
	v_lshl_add_u64 v[14:15], v[14:15], 0, v[158:159]
	global_load_dwordx4 v[248:251], v[14:15], off offset:1536
	v_mov_b64_e32 v[34:35], s[38:39]
	v_mov_b32_e32 v97, v1
	s_waitcnt vmcnt(19)
; DI f32x16 mfma(bf16x8 a, bf16x8 b, f32x16 c) { return __builtin_amdgcn_mfma_f32_32x32x16_bf16(a, b, c, 0, 0, 0); }
; DI void phase_mixb(const Prm& p, unsigned char* smem_raw, int S, int lgS, int& base) {
;     ...
;     for (int tt = 0; tt < 5; ++tt) {
; #pragma unroll
;       for (int e = 0; e < 4; ++e) {
;         const int c = lane + 64 * e, key = c >> 3, dch = c & 7;
;         int ik = i0 - 64 + 32 * tt + key;
;         ik = min(max(ik, 0), L - 1);
;         const u32x4 raw = *(const u32x4*)(p.bqkv + (size_t)(tokbase + (ik << lgd)) * 1152 + 768 + hc + dch * 8);
; #pragma unroll
;         for (int jj = 0; jj < 4; ++jj) {
;           vt[(dch * 8 + 2 * jj) * 40 + key] = (u16)(raw[jj] & 0xffffu);
;           vt[(dch * 8 + 2 * jj + 1) * 40 + key] = (u16)(raw[jj] >> 16);
;         }
;       }
;       __syncthreads();
; #pragma unroll
;       for (int u = 0; u < 2; ++u) {
;         u32x4 pk;
; #pragma unroll
;         for (int jj = 0; jj < 4; ++jj) pk[jj] = pack2(sc[tt][8 * u + 2 * jj], sc[tt][8 * u + 2 * jj + 1]);
;         const bf16x8 pf = __builtin_bit_cast(bf16x8, pk);
; #pragma unroll
;         for (int dt = 0; dt < 2; ++dt) {
;           const u16* vp = vt + (dt * 32 + lr) * 40 + 16 * u + 4 * lh;
;           u32x4 vv;
;           const u32x2 lo = *(const u32x2*)vp, hi = *(const u32x2*)(vp + 8);
;           vv[0] = lo[0]; vv[1] = lo[1]; vv[2] = hi[0]; vv[3] = hi[1];
;           oacc[dt] = mfma(__builtin_bit_cast(bf16x8, vv), pf, oacc[dt]);
;         }
;       }
;       __syncthreads();
	ds_write_b16 v109, v160 offset:3328
	ds_write_b16_d16_hi v109, v160 offset:3408
	ds_write_b16 v109, v161 offset:3488
	ds_write_b16_d16_hi v109, v161 offset:3568
	ds_write_b16 v109, v162 offset:3648
	ds_write_b16_d16_hi v109, v162 offset:3728
	ds_write_b16 v109, v163 offset:3808
	ds_write_b16_d16_hi v109, v163 offset:3888
	s_waitcnt vmcnt(18)
	ds_write_b16 v109, v164 offset:3344
	ds_write_b16_d16_hi v109, v164 offset:3424
	ds_write_b16 v109, v165 offset:3504
	ds_write_b16_d16_hi v109, v165 offset:3584
	ds_write_b16 v109, v166 offset:3664
	ds_write_b16_d16_hi v109, v166 offset:3744
	ds_write_b16 v109, v167 offset:3824
	ds_write_b16_d16_hi v109, v167 offset:3904
	s_waitcnt vmcnt(17)
	ds_write_b16 v109, v168 offset:3360
	ds_write_b16_d16_hi v109, v168 offset:3440
	ds_write_b16 v109, v169 offset:3520
	ds_write_b16_d16_hi v109, v169 offset:3600
	ds_write_b16 v109, v170 offset:3680
	ds_write_b16_d16_hi v109, v170 offset:3760
	ds_write_b16 v109, v171 offset:3840
	ds_write_b16_d16_hi v109, v171 offset:3920
	v_add_u32_e32 v91, 0x800, v129
	s_waitcnt vmcnt(16)
	ds_write_b16 v109, v172 offset:3376
	ds_write_b16_d16_hi v109, v172 offset:3456
	ds_write_b16 v109, v173 offset:3536
	ds_write_b16_d16_hi v109, v173 offset:3616
	ds_write_b16 v109, v174 offset:3696
	ds_write_b16_d16_hi v109, v174 offset:3776
	ds_write_b16 v109, v175 offset:3856
	ds_write_b16_d16_hi v109, v175 offset:3936
	s_waitcnt lgkmcnt(0)
	s_nop 0
	v_cvt_pk_bf16_f32 v2, v2, v3
	v_cvt_pk_bf16_f32 v3, v4, v5
	v_cvt_pk_bf16_f32 v4, v6, v7
	v_cvt_pk_bf16_f32 v5, v8, v9
	ds_read2_b64 v[6:9], v91 offset0:160 offset1:162
	ds_read2_b64 v[156:159], v91 offset0:164 offset1:166
	v_add_u32_e32 v82, 0x1000, v129
	s_waitcnt lgkmcnt(1)
	v_mfma_f32_32x32x16_bf16 v[18:33], v[6:9], v[2:5], 0
	ds_read2_b64 v[6:9], v82 offset0:224 offset1:226
	v_cvt_pk_bf16_f32 v148, v148, v149
	v_cvt_pk_bf16_f32 v149, v150, v151
	v_cvt_pk_bf16_f32 v150, v152, v153
	v_cvt_pk_bf16_f32 v151, v154, v155
	ds_read2_b64 v[152:155], v82 offset0:228 offset1:230
	s_waitcnt lgkmcnt(0)
	v_mfma_f32_32x32x16_bf16 v[2:17], v[6:9], v[2:5], 0
	s_nop 0
	v_cvt_pk_bf16_f32 v74, v74, v75
	v_cvt_pk_bf16_f32 v75, v76, v77
	v_cvt_pk_bf16_f32 v76, v78, v80
	v_cvt_pk_bf16_f32 v77, v81, v85
	v_cvt_pk_bf16_f32 v59, v59, v60
	v_mfma_f32_32x32x16_bf16 v[18:33], v[156:159], v[148:151], v[18:33]
	v_cvt_pk_bf16_f32 v60, v61, v63
	v_cvt_pk_bf16_f32 v61, v64, v68
	v_cvt_pk_bf16_f32 v58, v57, v58
	v_cvt_pk_bf16_f32 v51, v51, v52
	v_cvt_pk_bf16_f32 v52, v53, v54
	v_cvt_pk_bf16_f32 v53, v55, v56
	v_cvt_pk_bf16_f32 v50, v49, v50
	v_mfma_f32_32x32x16_bf16 v[2:17], v[152:155], v[148:151], v[2:17]
	s_waitcnt vmcnt(15)
	ds_write_b16 v109, v176 offset:3328
	ds_write_b16_d16_hi v109, v176 offset:3408
	ds_write_b16 v109, v177 offset:3488
	ds_write_b16_d16_hi v109, v177 offset:3568
	ds_write_b16 v109, v178 offset:3648
	ds_write_b16_d16_hi v109, v178 offset:3728
	ds_write_b16 v109, v179 offset:3808
	ds_write_b16_d16_hi v109, v179 offset:3888
	s_waitcnt vmcnt(14)
	ds_write_b16 v109, v180 offset:3344
	ds_write_b16_d16_hi v109, v180 offset:3424
	ds_write_b16 v109, v181 offset:3504
	ds_write_b16_d16_hi v109, v181 offset:3584
	ds_write_b16 v109, v182 offset:3664
	ds_write_b16_d16_hi v109, v182 offset:3744
	ds_write_b16 v109, v183 offset:3824
	ds_write_b16_d16_hi v109, v183 offset:3904
	s_waitcnt vmcnt(13)
	ds_write_b16 v109, v184 offset:3360
	ds_write_b16_d16_hi v109, v184 offset:3440
	ds_write_b16 v109, v185 offset:3520
	ds_write_b16_d16_hi v109, v185 offset:3600
	ds_write_b16 v109, v186 offset:3680
	ds_write_b16_d16_hi v109, v186 offset:3760
	ds_write_b16 v109, v187 offset:3840
	ds_write_b16_d16_hi v109, v187 offset:3920
	s_waitcnt vmcnt(12)
	ds_write_b16 v109, v188 offset:3376
	ds_write_b16_d16_hi v109, v188 offset:3456
	ds_write_b16 v109, v189 offset:3536
	ds_write_b16_d16_hi v109, v189 offset:3616
	ds_write_b16 v109, v190 offset:3696
	ds_write_b16_d16_hi v109, v190 offset:3776
	ds_write_b16 v109, v191 offset:3856
	ds_write_b16_d16_hi v109, v191 offset:3936
	s_waitcnt lgkmcnt(0)
	s_nop 0
	v_cvt_pk_bf16_f32 v150, v144, v145
	v_cvt_pk_bf16_f32 v151, v146, v147
	ds_read2_b64 v[144:147], v91 offset0:160 offset1:162
	ds_read2_b64 v[152:155], v91 offset0:164 offset1:166
	v_cvt_pk_bf16_f32 v148, v137, v140
	v_cvt_pk_bf16_f32 v149, v141, v143
	s_waitcnt lgkmcnt(1)
	s_nop 0
	v_mfma_f32_32x32x16_bf16 v[18:33], v[144:147], v[148:151], v[18:33]
	ds_read2_b64 v[144:147], v82 offset0:224 offset1:226
	ds_bpermute_b32 v40, v106, v39
	v_cvt_pk_bf16_f32 v43, v43, v44
	v_cvt_pk_bf16_f32 v44, v45, v46
	v_cvt_pk_bf16_f32 v45, v47, v48
	v_cvt_pk_bf16_f32 v42, v41, v42
	s_waitcnt lgkmcnt(1)
	v_mfma_f32_32x32x16_bf16 v[2:17], v[144:147], v[148:151], v[2:17]
	v_cvt_pk_bf16_f32 v145, v134, v135
	v_cvt_pk_bf16_f32 v146, v136, v138
	ds_read2_b64 v[134:137], v82 offset0:228 offset1:230
	v_cvt_pk_bf16_f32 v144, v92, v93
	v_cvt_pk_bf16_f32 v147, v139, v142
	s_waitcnt lgkmcnt(0)
	s_nop 0
	v_mfma_f32_32x32x16_bf16 v[2:17], v[134:137], v[144:147], v[2:17]
	s_nop 0
	s_waitcnt vmcnt(11)
	ds_write_b16 v109, v192 offset:3328
	ds_write_b16_d16_hi v109, v192 offset:3408
	ds_write_b16 v109, v193 offset:3488
	ds_write_b16_d16_hi v109, v193 offset:3568
	ds_write_b16 v109, v194 offset:3648
	ds_write_b16_d16_hi v109, v194 offset:3728
	ds_write_b16 v109, v195 offset:3808
	ds_write_b16_d16_hi v109, v195 offset:3888
	s_waitcnt vmcnt(10)
	ds_write_b16 v109, v196 offset:3344
	ds_write_b16_d16_hi v109, v196 offset:3424
	ds_write_b16 v109, v197 offset:3504
	ds_write_b16_d16_hi v109, v197 offset:3584
	ds_write_b16 v109, v198 offset:3664
	ds_write_b16_d16_hi v109, v198 offset:3744
	ds_write_b16 v109, v199 offset:3824
	ds_write_b16_d16_hi v109, v199 offset:3904
	s_waitcnt vmcnt(9)
; DI f32x16 mfma(bf16x8 a, bf16x8 b, f32x16 c) { return __builtin_amdgcn_mfma_f32_32x32x16_bf16(a, b, c, 0, 0, 0); }
; DI void phase_mixb(const Prm& p, unsigned char* smem_raw, int S, int lgS, int& base) {
;     ...
;     for (int tt = 0; tt < 5; ++tt) {
; #pragma unroll
;       for (int e = 0; e < 4; ++e) {
;         const int c = lane + 64 * e, key = c >> 3, dch = c & 7;
;         int ik = i0 - 64 + 32 * tt + key;
;         ik = min(max(ik, 0), L - 1);
;         const u32x4 raw = *(const u32x4*)(p.bqkv + (size_t)(tokbase + (ik << lgd)) * 1152 + 768 + hc + dch * 8);
; #pragma unroll
;         for (int jj = 0; jj < 4; ++jj) {
;           vt[(dch * 8 + 2 * jj) * 40 + key] = (u16)(raw[jj] & 0xffffu);
;           vt[(dch * 8 + 2 * jj + 1) * 40 + key] = (u16)(raw[jj] >> 16);
;         }
;       }
;       __syncthreads();
; #pragma unroll
;       for (int u = 0; u < 2; ++u) {
;         u32x4 pk;
; #pragma unroll
;         for (int jj = 0; jj < 4; ++jj) pk[jj] = pack2(sc[tt][8 * u + 2 * jj], sc[tt][8 * u + 2 * jj + 1]);
;         const bf16x8 pf = __builtin_bit_cast(bf16x8, pk);
; #pragma unroll
;         for (int dt = 0; dt < 2; ++dt) {
;           const u16* vp = vt + (dt * 32 + lr) * 40 + 16 * u + 4 * lh;
;           u32x4 vv;
;           const u32x2 lo = *(const u32x2*)vp, hi = *(const u32x2*)(vp + 8);
;           vv[0] = lo[0]; vv[1] = lo[1]; vv[2] = hi[0]; vv[3] = hi[1];
;           oacc[dt] = mfma(__builtin_bit_cast(bf16x8, vv), pf, oacc[dt]);
;         }
;       }
;       __syncthreads();
	ds_write_b16 v109, v200 offset:3360
	ds_write_b16_d16_hi v109, v200 offset:3440
	ds_write_b16 v109, v201 offset:3520
	ds_write_b16_d16_hi v109, v201 offset:3600
	ds_write_b16 v109, v202 offset:3680
	ds_write_b16_d16_hi v109, v202 offset:3760
	ds_write_b16 v109, v203 offset:3840
	ds_write_b16_d16_hi v109, v203 offset:3920
	v_mfma_f32_32x32x16_bf16 v[18:33], v[152:155], v[144:147], v[18:33]
	s_waitcnt vmcnt(8)
	ds_write_b16 v109, v204 offset:3376
	ds_write_b16_d16_hi v109, v204 offset:3456
	ds_write_b16 v109, v205 offset:3536
	ds_write_b16_d16_hi v109, v205 offset:3616
	ds_write_b16 v109, v206 offset:3696
	ds_write_b16_d16_hi v109, v206 offset:3776
	ds_write_b16 v109, v207 offset:3856
	ds_write_b16_d16_hi v109, v207 offset:3936
	s_waitcnt lgkmcnt(0)
	s_nop 0
	v_cvt_pk_bf16_f32 v135, v84, v86
	v_cvt_pk_bf16_f32 v136, v87, v88
	v_cvt_pk_bf16_f32 v137, v89, v90
	ds_read2_b64 v[86:89], v91 offset0:160 offset1:162
	ds_read2_b64 v[138:141], v91 offset0:164 offset1:166
	v_cvt_pk_bf16_f32 v134, v79, v83
	ds_read2_b64 v[78:81], v82 offset0:228 offset1:230
	s_waitcnt lgkmcnt(2)
	v_mfma_f32_32x32x16_bf16 v[18:33], v[86:89], v[134:137], v[18:33]
	ds_read2_b64 v[86:89], v82 offset0:224 offset1:226
	s_waitcnt lgkmcnt(0)
	s_nop 0
	v_readlane_b32 s37, v253, 25
	v_mfma_f32_32x32x16_bf16 v[2:17], v[86:89], v[134:137], v[2:17]
	v_readlane_b32 s40, v253, 28
	v_readlane_b32 s41, v253, 29
	v_readlane_b32 s42, v253, 30
	v_readlane_b32 s43, v253, 31
	v_readlane_b32 s44, v253, 32
	v_readlane_b32 s45, v253, 33
	v_readlane_b32 s46, v253, 34
	v_mfma_f32_32x32x16_bf16 v[18:33], v[138:141], v[74:77], v[18:33]
	v_readlane_b32 s47, v253, 35
	v_readlane_b32 s48, v253, 36
	v_readlane_b32 s49, v253, 37
	v_readlane_b32 s50, v253, 38
	v_readlane_b32 s51, v253, 39
	v_mfma_f32_32x32x16_bf16 v[2:17], v[78:81], v[74:77], v[2:17]
	s_waitcnt vmcnt(7)
	ds_write_b16 v109, v208 offset:3328
	ds_write_b16_d16_hi v109, v208 offset:3408
	ds_write_b16 v109, v209 offset:3488
	ds_write_b16_d16_hi v109, v209 offset:3568
	ds_write_b16 v109, v210 offset:3648
	ds_write_b16_d16_hi v109, v210 offset:3728
	ds_write_b16 v109, v211 offset:3808
	ds_write_b16_d16_hi v109, v211 offset:3888
	s_waitcnt vmcnt(6)
	ds_write_b16 v109, v212 offset:3344
	ds_write_b16_d16_hi v109, v212 offset:3424
	ds_write_b16 v109, v213 offset:3504
	ds_write_b16_d16_hi v109, v213 offset:3584
	ds_write_b16 v109, v214 offset:3664
	ds_write_b16_d16_hi v109, v214 offset:3744
	ds_write_b16 v109, v215 offset:3824
	ds_write_b16_d16_hi v109, v215 offset:3904
	s_waitcnt vmcnt(5)
	ds_write_b16 v109, v216 offset:3360
	ds_write_b16_d16_hi v109, v216 offset:3440
	ds_write_b16 v109, v217 offset:3520
	ds_write_b16_d16_hi v109, v217 offset:3600
	ds_write_b16 v109, v218 offset:3680
	ds_write_b16_d16_hi v109, v218 offset:3760
	ds_write_b16 v109, v219 offset:3840
	ds_write_b16_d16_hi v109, v219 offset:3920
	s_waitcnt vmcnt(4)
	ds_write_b16 v109, v220 offset:3376
	ds_write_b16_d16_hi v109, v220 offset:3456
	ds_write_b16 v109, v221 offset:3536
	ds_write_b16_d16_hi v109, v221 offset:3616
	ds_write_b16 v109, v222 offset:3696
	ds_write_b16_d16_hi v109, v222 offset:3776
	ds_write_b16 v109, v223 offset:3856
	ds_write_b16_d16_hi v109, v223 offset:3936
	s_waitcnt lgkmcnt(0)
	s_nop 0
	v_cvt_pk_bf16_f32 v76, v70, v71
	v_cvt_pk_bf16_f32 v77, v72, v73
	ds_read2_b64 v[70:73], v91 offset0:160 offset1:162
	ds_read2_b64 v[78:81], v91 offset0:164 offset1:166
	v_cvt_pk_bf16_f32 v74, v62, v65
	v_cvt_pk_bf16_f32 v75, v67, v69
	ds_read2_b64 v[62:65], v82 offset0:228 offset1:230
	s_waitcnt lgkmcnt(2)
	v_mfma_f32_32x32x16_bf16 v[18:33], v[70:73], v[74:77], v[18:33]
	ds_read2_b64 v[70:73], v82 offset0:224 offset1:226
	s_waitcnt lgkmcnt(0)
	s_nop 0
	v_mfma_f32_32x32x16_bf16 v[2:17], v[70:73], v[74:77], v[2:17]
	v_mfma_f32_32x32x16_bf16 v[18:33], v[78:81], v[58:61], v[18:33]
	v_mfma_f32_32x32x16_bf16 v[2:17], v[62:65], v[58:61], v[2:17]
	s_waitcnt vmcnt(3)
	ds_write_b16 v109, v226 offset:3328
	ds_write_b16_d16_hi v109, v226 offset:3408
	ds_write_b16 v109, v227 offset:3488
	ds_write_b16_d16_hi v109, v227 offset:3568
	ds_write_b16 v109, v228 offset:3648
	ds_write_b16_d16_hi v109, v228 offset:3728
	ds_write_b16 v109, v229 offset:3808
	ds_write_b16_d16_hi v109, v229 offset:3888
	s_waitcnt vmcnt(2)
; DI f32x16 mfma(bf16x8 a, bf16x8 b, f32x16 c) { return __builtin_amdgcn_mfma_f32_32x32x16_bf16(a, b, c, 0, 0, 0); }
; DI void phase_mixb(const Prm& p, unsigned char* smem_raw, int S, int lgS, int& base) {
;     ...
;           const u32x2 lo = *(const u32x2*)vp, hi = *(const u32x2*)(vp + 8);
;           vv[0] = lo[0]; vv[1] = lo[1]; vv[2] = hi[0]; vv[3] = hi[1];
;           oacc[dt] = mfma(__builtin_bit_cast(bf16x8, vv), pf, oacc[dt]);
;         }
;       }
;       __syncthreads();
;     }
;     const float inv = 1.f / sum;
; #pragma unroll
;     for (int dt = 0; dt < 2; ++dt)
; #pragma unroll
;       for (int q = 0; q < 4; ++q) {
;         float4 o;
;         o.x = oacc[dt][4 * q] * inv; o.y = oacc[dt][4 * q + 1] * inv; o.z = oacc[dt][4 * q + 2] * inv; o.w = oacc[dt][4 * q + 3] * inv;
;         *(float4*)(p.og + (size_t)qtok * 384 + hc + dt * 32 + 8 * q + 4 * lh) = o;
;       }
;     if (lh == 0) p.lse[(size_t)qtok * 6 + hd] = (mx + __log2f(sum)) * LN2;
	ds_write_b16 v109, v234 offset:3344
	ds_write_b16_d16_hi v109, v234 offset:3424
	ds_write_b16 v109, v235 offset:3504
	ds_write_b16_d16_hi v109, v235 offset:3584
	ds_write_b16 v109, v236 offset:3664
	ds_write_b16_d16_hi v109, v236 offset:3744
	ds_write_b16 v109, v237 offset:3824
	ds_write_b16_d16_hi v109, v237 offset:3904
	s_waitcnt vmcnt(1)
	ds_write_b16 v109, v244 offset:3360
	ds_write_b16_d16_hi v109, v244 offset:3440
	ds_write_b16 v109, v245 offset:3520
	ds_write_b16_d16_hi v109, v245 offset:3600
	ds_write_b16 v109, v246 offset:3680
	ds_write_b16_d16_hi v109, v246 offset:3760
	ds_write_b16 v109, v247 offset:3840
	ds_write_b16_d16_hi v109, v247 offset:3920
	s_waitcnt vmcnt(0)
	ds_write_b16 v109, v248 offset:3376
	ds_write_b16_d16_hi v109, v248 offset:3456
	ds_write_b16 v109, v249 offset:3536
	ds_write_b16_d16_hi v109, v249 offset:3616
	ds_write_b16 v109, v250 offset:3696
	ds_write_b16_d16_hi v109, v250 offset:3776
	ds_write_b16 v109, v251 offset:3856
	ds_write_b16_d16_hi v109, v251 offset:3936
	s_waitcnt lgkmcnt(0)
	s_nop 0
	ds_read2_b64 v[54:57], v91 offset0:160 offset1:162
	ds_read2_b64 v[58:61], v91 offset0:164 offset1:166
	s_waitcnt lgkmcnt(1)
	v_mfma_f32_32x32x16_bf16 v[18:33], v[54:57], v[50:53], v[18:33]
	ds_read2_b64 v[54:57], v82 offset0:224 offset1:226
	ds_read2_b64 v[46:49], v82 offset0:228 offset1:230
	v_add_f32_e32 v34, v39, v40
	v_div_scale_f32 v35, s[2:3], v34, v34, 1.0
	v_rcp_f32_e32 v37, v35
	s_waitcnt lgkmcnt(0)
	v_mfma_f32_32x32x16_bf16 v[2:17], v[54:57], v[50:53], v[2:17]
	v_fma_f32 v38, -v35, v37, 1.0
	v_fmac_f32_e32 v37, v38, v37
	v_div_scale_f32 v38, vcc, 1.0, v34, 1.0
	v_mul_f32_e32 v39, v38, v37
	v_fma_f32 v40, -v35, v39, v38
	v_fmac_f32_e32 v39, v40, v37
	v_mfma_f32_32x32x16_bf16 v[18:33], v[58:61], v[42:45], v[18:33]
	v_fma_f32 v35, -v35, v39, v38
	v_mov_b64_e32 v[40:41], s[24:25]
	v_div_fmas_f32 v35, v35, v37, v39
	v_mad_i64_i32 v[40:41], s[2:3], v130, s83, v[40:41]
	v_div_fixup_f32 v38, v35, v34, 1.0
	v_lshl_add_u64 v[40:41], v[100:101], 2, v[40:41]
	v_mfma_f32_32x32x16_bf16 v[2:17], v[46:49], v[42:45], v[2:17]
	v_lshlrev_b32_e32 v42, 2, v94
	v_mov_b32_e32 v43, v1
	v_lshl_add_u64 v[40:41], v[40:41], 0, v[42:43]
	s_nop 1
	v_mul_f32_e64 v18, v38, v18
	v_mul_f32_e64 v19, v38, v19
	v_pk_mul_f32 v[20:21], v[38:39], v[20:21] op_sel_hi:[0,1]
	s_nop 0
	s_nop 2
	v_pk_mul_f32 v[2:3], v[38:39], v[2:3] op_sel_hi:[0,1]
	v_pk_mul_f32 v[4:5], v[38:39], v[4:5] op_sel_hi:[0,1]
	global_store_dwordx4 v[40:41], v[18:21], off
	global_store_dwordx4 v[40:41], v[2:5], off offset:128
	s_nop 0
	v_pk_mul_f32 v[18:19], v[38:39], v[22:23] op_sel_hi:[0,1]
	v_pk_mul_f32 v[20:21], v[38:39], v[24:25] op_sel_hi:[0,1]
	v_pk_mul_f32 v[2:3], v[38:39], v[6:7] op_sel_hi:[0,1]
	v_pk_mul_f32 v[4:5], v[38:39], v[8:9] op_sel_hi:[0,1]
	global_store_dwordx4 v[40:41], v[18:21], off offset:32
	global_store_dwordx4 v[40:41], v[2:5], off offset:160
	s_nop 0
	v_pk_mul_f32 v[18:19], v[38:39], v[26:27] op_sel_hi:[0,1]
	v_pk_mul_f32 v[20:21], v[38:39], v[28:29] op_sel_hi:[0,1]
	v_pk_mul_f32 v[2:3], v[38:39], v[10:11] op_sel_hi:[0,1]
	v_pk_mul_f32 v[4:5], v[38:39], v[12:13] op_sel_hi:[0,1]
	global_store_dwordx4 v[40:41], v[18:21], off offset:64
	global_store_dwordx4 v[40:41], v[2:5], off offset:192
	s_nop 0
	v_pk_mul_f32 v[18:19], v[38:39], v[30:31] op_sel_hi:[0,1]
	v_pk_mul_f32 v[20:21], v[38:39], v[32:33] op_sel_hi:[0,1]
	v_pk_mul_f32 v[2:3], v[38:39], v[14:15] op_sel_hi:[0,1]
	v_pk_mul_f32 v[4:5], v[38:39], v[16:17] op_sel_hi:[0,1]
	global_store_dwordx4 v[40:41], v[18:21], off offset:96
	global_store_dwordx4 v[40:41], v[2:5], off offset:224
	s_and_saveexec_b64 s[2:3], s[0:1]
	s_cbranch_execz .LBB0_1836
	v_log_f32_e32 v4, v34
	v_ashrrev_i32_e32 v99, 31, v98
	v_mad_i64_i32 v[2:3], s[4:5], v130, 24, s[26:27]
	v_add_f32_e32 v4, v36, v4
	v_mul_f32_e32 v4, 0x3f317218, v4
	v_lshl_add_u64 v[2:3], v[98:99], 2, v[2:3]
	global_store_dword v[2:3], v4, off
	s_branch .LBB0_1836
